# layer-0 MLP2 epilogue does not write the bf16 residual copy (next layer is the pool mixer, which reads only the f32 stream and the ssq partials)
# baseline (speedup 1.0000x reference)
.LBB0_1696:
	v_readlane_b32 s40, v251, 47
	s_nop 0
	s_cmp_eq_u32 s40, 3
	s_cbranch_scc1 .Lres_mlp2_last
	s_cmp_eq_u32 s40, 0
	s_cbranch_scc1 .Lres_mlp2_l0
	v_readfirstlane_b32 s40, v204
	s_lshr_b32 s40, s40, 6
	s_and_b32 s41, s40, 1
	s_bfe_u32 s42, s40, 0x10001
	s_lshr_b32 s43, s40, 2
	s_lshl_b32 s44, s4, 1
	s_add_i32 s44, s44, s42
	s_lshl_b32 s45, s44, 7
	s_lshl_b32 s46, s41, 6
	s_add_i32 s45, s45, s46
	s_lshl_b32 s46, s43, 7
	s_add_i32 s46, s46, s2
	s_lshl_b32 s47, s44, 1
	s_add_i32 s47, s47, s41
	v_readlane_b32 s36, v250, 9
	v_readlane_b32 s37, v250, 10
	s_mov_b64 s[38:39], s[36:37]
	v_readlane_b32 s50, v250, 11
	v_readlane_b32 s51, v250, 12
	s_add_u32 s34, s50, 0xf900000
	s_addc_u32 s35, s51, 0
	s_add_u32 s50, s50, 0x5800000
	s_addc_u32 s51, s51, 0
	s_lshl_b32 s48, s46, 12
	s_lshl_b32 s49, s45, 2
	s_add_u32 s48, s48, s49
	s_add_u32 s36, s36, s48
	s_addc_u32 s37, s37, 0
	s_add_u32 s38, s38, s48
	s_addc_u32 s39, s39, 0
	s_lshr_b32 s48, s48, 1
	s_add_u32 s50, s50, s48
	s_addc_u32 s51, s51, 0
	s_lshl_b32 s48, s46, 6
	s_lshl_b32 s49, s47, 2
	s_add_u32 s48, s48, s49
	s_add_u32 s34, s34, s48
	s_addc_u32 s35, s35, 0
	v_and_b32_e32 v249, 63, v204
	v_and_b32_e32 v170, 31, v249
	v_lshrrev_b32_e32 v171, 5, v249
	v_and_b32_e32 v208, 15, v249
	v_lshrrev_b32_e32 v209, 4, v249
	s_lshl_b32 s40, s40, 14
	v_and_b32_e32 v238, 15, v170
	v_xor_b32_e32 v238, v238, v171
	v_lshl_add_u32 v239, v170, 8, s40
	v_xor_b32_e32 v228, 0, v238
	v_lshl_add_u32 v228, v228, 4, v239
	v_xor_b32_e32 v229, 2, v238
	v_lshl_add_u32 v229, v229, 4, v239
	v_xor_b32_e32 v230, 4, v238
	v_lshl_add_u32 v230, v230, 4, v239
	v_xor_b32_e32 v231, 6, v238
	v_lshl_add_u32 v231, v231, 4, v239
	v_xor_b32_e32 v232, 8, v238
	v_lshl_add_u32 v232, v232, 4, v239
	v_xor_b32_e32 v233, 10, v238
	v_lshl_add_u32 v233, v233, 4, v239
	v_xor_b32_e32 v234, 12, v238
	v_lshl_add_u32 v234, v234, 4, v239
	v_xor_b32_e32 v235, 14, v238
	v_lshl_add_u32 v235, v235, 4, v239
	v_lshl_add_u32 v239, v209, 8, s40
	v_add_u32_e32 v210, 0, v209
	v_xor_b32_e32 v210, v210, v208
	v_lshl_add_u32 v210, v210, 4, v239
	v_add_u32_e32 v211, 4, v209
	v_xor_b32_e32 v211, v211, v208
	v_lshl_add_u32 v211, v211, 4, v239
	v_add_u32_e32 v215, 8, v209
	v_xor_b32_e32 v215, v215, v208
	v_lshl_add_u32 v215, v215, 4, v239
	v_add_u32_e32 v237, 12, v209
	v_xor_b32_e32 v237, v237, v208
	v_lshl_add_u32 v237, v237, 4, v239
	v_lshlrev_b32_e32 v247, 12, v209
	v_lshl_add_u32 v247, v208, 4, v247
	v_lshrrev_b32_e32 v248, 1, v247
	v_lshlrev_b32_e32 v249, 6, v209
	s_mov_b32 s48, 0x00010001
	s_mov_b32 s49, 0x00010001
	global_load_dwordx4 v[130:133], v247, s[36:37]
	s_add_u32 s36, s36, 0x4000
	s_addc_u32 s37, s37, 0
	global_load_dwordx4 v[134:137], v247, s[36:37]
	s_add_u32 s36, s36, 0x4000
	s_addc_u32 s37, s37, 0
	global_load_dwordx4 v[138:141], v247, s[36:37]
	s_add_u32 s36, s36, 0x4000
	s_addc_u32 s37, s37, 0
	global_load_dwordx4 v[142:145], v247, s[36:37]
	s_add_u32 s36, s36, 0x4000
	s_addc_u32 s37, s37, 0
	global_load_dwordx4 v[146:149], v247, s[36:37]
	s_add_u32 s36, s36, 0x4000
	s_addc_u32 s37, s37, 0
	global_load_dwordx4 v[150:153], v247, s[36:37]
	s_add_u32 s36, s36, 0x4000
	s_addc_u32 s37, s37, 0
	global_load_dwordx4 v[154:157], v247, s[36:37]
	s_add_u32 s36, s36, 0x4000
	s_addc_u32 s37, s37, 0
	global_load_dwordx4 v[158:161], v247, s[36:37]
	s_add_u32 s36, s36, 0x4000
	s_addc_u32 s37, s37, 0
	global_load_dwordx4 v[162:165], v247, s[36:37]
	s_add_u32 s36, s36, 0x4000
	s_addc_u32 s37, s37, 0
	global_load_dwordx4 v[166:169], v247, s[36:37]
	s_add_u32 s36, s36, 0x4000
	s_addc_u32 s37, s37, 0
	global_load_dwordx4 v[192:195], v247, s[36:37]
	s_add_u32 s36, s36, 0x4000
	s_addc_u32 s37, s37, 0
	global_load_dwordx4 v[196:199], v247, s[36:37]
	s_add_u32 s36, s36, 0x4000
	s_addc_u32 s37, s37, 0
	global_load_dwordx4 v[200:203], v247, s[36:37]
	s_add_u32 s36, s36, 0x4000
	s_addc_u32 s37, s37, 0
	global_load_dwordx4 v[216:219], v247, s[36:37]
	s_add_u32 s36, s36, 0x4000
	s_addc_u32 s37, s37, 0
	global_load_dwordx4 v[220:223], v247, s[36:37]
	s_add_u32 s36, s36, 0x4000
	s_addc_u32 s37, s37, 0
	global_load_dwordx4 v[224:227], v247, s[36:37]
	s_add_u32 s36, s36, 0x4000
	s_addc_u32 s37, s37, 0
	ds_write_b128 v228, v[66:69]
	ds_write_b128 v229, v[70:73]
	ds_write_b128 v230, v[74:77]
	ds_write_b128 v231, v[78:81]
	ds_write_b128 v232, v[114:117]
	ds_write_b128 v233, v[118:121]
	ds_write_b128 v234, v[122:125]
	ds_write_b128 v235, v[126:129]
	ds_write_b128 v228, v[82:85] offset:8192
	ds_write_b128 v229, v[86:89] offset:8192
	ds_write_b128 v230, v[90:93] offset:8192
	ds_write_b128 v231, v[94:97] offset:8192
	ds_write_b128 v232, v[98:101] offset:8192
	ds_write_b128 v233, v[102:105] offset:8192
	ds_write_b128 v234, v[106:109] offset:8192
	ds_write_b128 v235, v[110:113] offset:8192
	global_load_dwordx4 v[66:69], v247, s[36:37]
	s_add_u32 s36, s36, 0x4000
	s_addc_u32 s37, s37, 0
	global_load_dwordx4 v[70:73], v247, s[36:37]
	s_add_u32 s36, s36, 0x4000
	s_addc_u32 s37, s37, 0
	global_load_dwordx4 v[74:77], v247, s[36:37]
	s_add_u32 s36, s36, 0x4000
	s_addc_u32 s37, s37, 0
	global_load_dwordx4 v[78:81], v247, s[36:37]
	s_add_u32 s36, s36, 0x4000
	s_addc_u32 s37, s37, 0
	global_load_dwordx4 v[114:117], v247, s[36:37]
	s_add_u32 s36, s36, 0x4000
	s_addc_u32 s37, s37, 0
	global_load_dwordx4 v[118:121], v247, s[36:37]
	s_add_u32 s36, s36, 0x4000
	s_addc_u32 s37, s37, 0
	global_load_dwordx4 v[122:125], v247, s[36:37]
	s_add_u32 s36, s36, 0x4000
	s_addc_u32 s37, s37, 0
	global_load_dwordx4 v[126:129], v247, s[36:37]
	s_add_u32 s36, s36, 0x4000
	s_addc_u32 s37, s37, 0
	global_load_dwordx4 v[82:85], v247, s[36:37]
	s_add_u32 s36, s36, 0x4000
	s_addc_u32 s37, s37, 0
	global_load_dwordx4 v[86:89], v247, s[36:37]
	s_add_u32 s36, s36, 0x4000
	s_addc_u32 s37, s37, 0
	global_load_dwordx4 v[90:93], v247, s[36:37]
	s_add_u32 s36, s36, 0x4000
	s_addc_u32 s37, s37, 0
	global_load_dwordx4 v[94:97], v247, s[36:37]
	s_add_u32 s36, s36, 0x4000
	s_addc_u32 s37, s37, 0
	global_load_dwordx4 v[98:101], v247, s[36:37]
	s_add_u32 s36, s36, 0x4000
	s_addc_u32 s37, s37, 0
	global_load_dwordx4 v[102:105], v247, s[36:37]
	s_add_u32 s36, s36, 0x4000
	s_addc_u32 s37, s37, 0
	global_load_dwordx4 v[106:109], v247, s[36:37]
	s_add_u32 s36, s36, 0x4000
	s_addc_u32 s37, s37, 0
	global_load_dwordx4 v[110:113], v247, s[36:37]
	s_add_u32 s36, s36, 0x4000
	s_addc_u32 s37, s37, 0
	s_waitcnt lgkmcnt(0)
	ds_read_b128 v[228:231], v210 offset:0
	ds_read_b128 v[238:241], v211 offset:1024
	s_waitcnt vmcnt(31) lgkmcnt(1)
	v_pk_add_f32 v[130:131], v[228:229], v[130:131]
	v_pk_add_f32 v[132:133], v[230:231], v[132:133]
	v_pk_mul_f32 v[232:233], v[130:131], v[130:131]
	v_pk_mul_f32 v[234:235], v[132:133], v[132:133]
	ds_read_b128 v[228:231], v215 offset:2048
	v_add_f32_e32 v236, v232, v233
	v_add_f32_e32 v236, v234, v236
	v_add_f32_e32 v236, v235, v236
	global_store_dwordx4 v247, v[130:133], s[38:39]
	v_cvt_pk_bf16_f32 v232, v130, v131
	v_cvt_pk_bf16_f32 v233, v132, v133
	v_add_f32_dpp v236, v236, v236 quad_perm:[1,0,3,2] row_mask:0xf bank_mask:0xf
	global_store_dwordx2 v248, v[232:233], s[50:51]
	s_add_u32 s38, s38, 0x4000
	s_addc_u32 s39, s39, 0
	v_add_f32_dpp v236, v236, v236 quad_perm:[2,3,0,1] row_mask:0xf bank_mask:0xf
	s_add_u32 s50, s50, 0x2000
	s_addc_u32 s51, s51, 0
	v_add_f32_dpp v236, v236, v236 row_half_mirror row_mask:0xf bank_mask:0xf
	s_nop 1
	v_add_f32_dpp v236, v236, v236 row_mirror row_mask:0xf bank_mask:0xf
	s_mov_b64 exec, s[48:49]
	global_store_dword v249, v236, s[34:35] offset:0
	s_mov_b64 exec, -1
	s_waitcnt vmcnt(33) lgkmcnt(1)
	v_pk_add_f32 v[134:135], v[238:239], v[134:135]
	v_pk_add_f32 v[136:137], v[240:241], v[136:137]
	v_pk_mul_f32 v[242:243], v[134:135], v[134:135]
	v_pk_mul_f32 v[244:245], v[136:137], v[136:137]
	ds_read_b128 v[238:241], v237 offset:3072
	v_add_f32_e32 v246, v242, v243
	v_add_f32_e32 v246, v244, v246
	v_add_f32_e32 v246, v245, v246
	global_store_dwordx4 v247, v[134:137], s[38:39]
	v_cvt_pk_bf16_f32 v242, v134, v135
	v_cvt_pk_bf16_f32 v243, v136, v137
	v_add_f32_dpp v246, v246, v246 quad_perm:[1,0,3,2] row_mask:0xf bank_mask:0xf
	global_store_dwordx2 v248, v[242:243], s[50:51]
	s_add_u32 s38, s38, 0x4000
	s_addc_u32 s39, s39, 0
	v_add_f32_dpp v246, v246, v246 quad_perm:[2,3,0,1] row_mask:0xf bank_mask:0xf
	s_add_u32 s50, s50, 0x2000
	s_addc_u32 s51, s51, 0
	v_add_f32_dpp v246, v246, v246 row_half_mirror row_mask:0xf bank_mask:0xf
	s_nop 1
	v_add_f32_dpp v246, v246, v246 row_mirror row_mask:0xf bank_mask:0xf
	s_mov_b64 exec, s[48:49]
	global_store_dword v249, v246, s[34:35] offset:256
	s_mov_b64 exec, -1
	s_waitcnt vmcnt(35) lgkmcnt(1)
	v_pk_add_f32 v[138:139], v[228:229], v[138:139]
	v_pk_add_f32 v[140:141], v[230:231], v[140:141]
	v_pk_mul_f32 v[232:233], v[138:139], v[138:139]
	v_pk_mul_f32 v[234:235], v[140:141], v[140:141]
	ds_read_b128 v[228:231], v210 offset:4096
	v_add_f32_e32 v236, v232, v233
	v_add_f32_e32 v236, v234, v236
	v_add_f32_e32 v236, v235, v236
	global_store_dwordx4 v247, v[138:141], s[38:39]
	v_cvt_pk_bf16_f32 v232, v138, v139
	v_cvt_pk_bf16_f32 v233, v140, v141
	v_add_f32_dpp v236, v236, v236 quad_perm:[1,0,3,2] row_mask:0xf bank_mask:0xf
	global_store_dwordx2 v248, v[232:233], s[50:51]
	s_add_u32 s38, s38, 0x4000
	s_addc_u32 s39, s39, 0
	v_add_f32_dpp v236, v236, v236 quad_perm:[2,3,0,1] row_mask:0xf bank_mask:0xf
	s_add_u32 s50, s50, 0x2000
	s_addc_u32 s51, s51, 0
	v_add_f32_dpp v236, v236, v236 row_half_mirror row_mask:0xf bank_mask:0xf
	s_nop 1
	v_add_f32_dpp v236, v236, v236 row_mirror row_mask:0xf bank_mask:0xf
	s_mov_b64 exec, s[48:49]
	global_store_dword v249, v236, s[34:35] offset:512
	s_mov_b64 exec, -1
	s_waitcnt vmcnt(37) lgkmcnt(1)
	v_pk_add_f32 v[142:143], v[238:239], v[142:143]
	v_pk_add_f32 v[144:145], v[240:241], v[144:145]
	v_pk_mul_f32 v[242:243], v[142:143], v[142:143]
	v_pk_mul_f32 v[244:245], v[144:145], v[144:145]
	ds_read_b128 v[238:241], v211 offset:5120
	v_add_f32_e32 v246, v242, v243
	v_add_f32_e32 v246, v244, v246
	v_add_f32_e32 v246, v245, v246
	global_store_dwordx4 v247, v[142:145], s[38:39]
	v_cvt_pk_bf16_f32 v242, v142, v143
	v_cvt_pk_bf16_f32 v243, v144, v145
	v_add_f32_dpp v246, v246, v246 quad_perm:[1,0,3,2] row_mask:0xf bank_mask:0xf
	global_store_dwordx2 v248, v[242:243], s[50:51]
	s_add_u32 s38, s38, 0x4000
	s_addc_u32 s39, s39, 0
	v_add_f32_dpp v246, v246, v246 quad_perm:[2,3,0,1] row_mask:0xf bank_mask:0xf
	s_add_u32 s50, s50, 0x2000
	s_addc_u32 s51, s51, 0
	v_add_f32_dpp v246, v246, v246 row_half_mirror row_mask:0xf bank_mask:0xf
	s_nop 1
	v_add_f32_dpp v246, v246, v246 row_mirror row_mask:0xf bank_mask:0xf
	s_mov_b64 exec, s[48:49]
	global_store_dword v249, v246, s[34:35] offset:768
	s_mov_b64 exec, -1
	s_waitcnt vmcnt(39) lgkmcnt(1)
	v_pk_add_f32 v[146:147], v[228:229], v[146:147]
	v_pk_add_f32 v[148:149], v[230:231], v[148:149]
	v_pk_mul_f32 v[232:233], v[146:147], v[146:147]
	v_pk_mul_f32 v[234:235], v[148:149], v[148:149]
	ds_read_b128 v[228:231], v215 offset:6144
	v_add_f32_e32 v236, v232, v233
	v_add_f32_e32 v236, v234, v236
	v_add_f32_e32 v236, v235, v236
	global_store_dwordx4 v247, v[146:149], s[38:39]
	v_cvt_pk_bf16_f32 v232, v146, v147
	v_cvt_pk_bf16_f32 v233, v148, v149
	v_add_f32_dpp v236, v236, v236 quad_perm:[1,0,3,2] row_mask:0xf bank_mask:0xf
	global_store_dwordx2 v248, v[232:233], s[50:51]
	s_add_u32 s38, s38, 0x4000
	s_addc_u32 s39, s39, 0
	v_add_f32_dpp v236, v236, v236 quad_perm:[2,3,0,1] row_mask:0xf bank_mask:0xf
	s_add_u32 s50, s50, 0x2000
	s_addc_u32 s51, s51, 0
	v_add_f32_dpp v236, v236, v236 row_half_mirror row_mask:0xf bank_mask:0xf
	s_nop 1
	v_add_f32_dpp v236, v236, v236 row_mirror row_mask:0xf bank_mask:0xf
	s_mov_b64 exec, s[48:49]
	global_store_dword v249, v236, s[34:35] offset:1024
	s_mov_b64 exec, -1
	s_waitcnt vmcnt(41) lgkmcnt(1)
	v_pk_add_f32 v[150:151], v[238:239], v[150:151]
	v_pk_add_f32 v[152:153], v[240:241], v[152:153]
	v_pk_mul_f32 v[242:243], v[150:151], v[150:151]
	v_pk_mul_f32 v[244:245], v[152:153], v[152:153]
	ds_read_b128 v[238:241], v237 offset:7168
	v_add_f32_e32 v246, v242, v243
	v_add_f32_e32 v246, v244, v246
	v_add_f32_e32 v246, v245, v246
	global_store_dwordx4 v247, v[150:153], s[38:39]
	v_cvt_pk_bf16_f32 v242, v150, v151
	v_cvt_pk_bf16_f32 v243, v152, v153
	v_add_f32_dpp v246, v246, v246 quad_perm:[1,0,3,2] row_mask:0xf bank_mask:0xf
	global_store_dwordx2 v248, v[242:243], s[50:51]
	s_add_u32 s38, s38, 0x4000
	s_addc_u32 s39, s39, 0
	v_add_f32_dpp v246, v246, v246 quad_perm:[2,3,0,1] row_mask:0xf bank_mask:0xf
	s_add_u32 s50, s50, 0x2000
	s_addc_u32 s51, s51, 0
	v_add_f32_dpp v246, v246, v246 row_half_mirror row_mask:0xf bank_mask:0xf
	s_nop 1
	v_add_f32_dpp v246, v246, v246 row_mirror row_mask:0xf bank_mask:0xf
	s_mov_b64 exec, s[48:49]
	global_store_dword v249, v246, s[34:35] offset:1280
	s_mov_b64 exec, -1
	s_waitcnt vmcnt(43) lgkmcnt(1)
	v_pk_add_f32 v[154:155], v[228:229], v[154:155]
	v_pk_add_f32 v[156:157], v[230:231], v[156:157]
	v_pk_mul_f32 v[232:233], v[154:155], v[154:155]
	v_pk_mul_f32 v[234:235], v[156:157], v[156:157]
	ds_read_b128 v[228:231], v210 offset:8192
	v_add_f32_e32 v236, v232, v233
	v_add_f32_e32 v236, v234, v236
	v_add_f32_e32 v236, v235, v236
	global_store_dwordx4 v247, v[154:157], s[38:39]
	v_cvt_pk_bf16_f32 v232, v154, v155
	v_cvt_pk_bf16_f32 v233, v156, v157
	v_add_f32_dpp v236, v236, v236 quad_perm:[1,0,3,2] row_mask:0xf bank_mask:0xf
	global_store_dwordx2 v248, v[232:233], s[50:51]
	s_add_u32 s38, s38, 0x4000
	s_addc_u32 s39, s39, 0
	v_add_f32_dpp v236, v236, v236 quad_perm:[2,3,0,1] row_mask:0xf bank_mask:0xf
	s_add_u32 s50, s50, 0x2000
	s_addc_u32 s51, s51, 0
	v_add_f32_dpp v236, v236, v236 row_half_mirror row_mask:0xf bank_mask:0xf
	s_nop 1
	v_add_f32_dpp v236, v236, v236 row_mirror row_mask:0xf bank_mask:0xf
	s_mov_b64 exec, s[48:49]
	global_store_dword v249, v236, s[34:35] offset:1536
	s_mov_b64 exec, -1
	s_waitcnt vmcnt(45) lgkmcnt(1)
	v_pk_add_f32 v[158:159], v[238:239], v[158:159]
	v_pk_add_f32 v[160:161], v[240:241], v[160:161]
	v_pk_mul_f32 v[242:243], v[158:159], v[158:159]
	v_pk_mul_f32 v[244:245], v[160:161], v[160:161]
	ds_read_b128 v[238:241], v211 offset:9216
	v_add_f32_e32 v246, v242, v243
	v_add_f32_e32 v246, v244, v246
	v_add_f32_e32 v246, v245, v246
	global_store_dwordx4 v247, v[158:161], s[38:39]
	v_cvt_pk_bf16_f32 v242, v158, v159
	v_cvt_pk_bf16_f32 v243, v160, v161
	v_add_f32_dpp v246, v246, v246 quad_perm:[1,0,3,2] row_mask:0xf bank_mask:0xf
	global_store_dwordx2 v248, v[242:243], s[50:51]
	s_add_u32 s38, s38, 0x4000
	s_addc_u32 s39, s39, 0
	v_add_f32_dpp v246, v246, v246 quad_perm:[2,3,0,1] row_mask:0xf bank_mask:0xf
	s_add_u32 s50, s50, 0x2000
	s_addc_u32 s51, s51, 0
	v_add_f32_dpp v246, v246, v246 row_half_mirror row_mask:0xf bank_mask:0xf
	s_nop 1
	v_add_f32_dpp v246, v246, v246 row_mirror row_mask:0xf bank_mask:0xf
	s_mov_b64 exec, s[48:49]
	global_store_dword v249, v246, s[34:35] offset:1792
	s_mov_b64 exec, -1
	s_waitcnt vmcnt(47) lgkmcnt(1)
	v_pk_add_f32 v[162:163], v[228:229], v[162:163]
	v_pk_add_f32 v[164:165], v[230:231], v[164:165]
	v_pk_mul_f32 v[232:233], v[162:163], v[162:163]
	v_pk_mul_f32 v[234:235], v[164:165], v[164:165]
	ds_read_b128 v[228:231], v215 offset:10240
	v_add_f32_e32 v236, v232, v233
	v_add_f32_e32 v236, v234, v236
	v_add_f32_e32 v236, v235, v236
	global_store_dwordx4 v247, v[162:165], s[38:39]
	v_cvt_pk_bf16_f32 v232, v162, v163
	v_cvt_pk_bf16_f32 v233, v164, v165
	v_add_f32_dpp v236, v236, v236 quad_perm:[1,0,3,2] row_mask:0xf bank_mask:0xf
	global_store_dwordx2 v248, v[232:233], s[50:51]
	s_add_u32 s38, s38, 0x4000
	s_addc_u32 s39, s39, 0
	v_add_f32_dpp v236, v236, v236 quad_perm:[2,3,0,1] row_mask:0xf bank_mask:0xf
	s_add_u32 s50, s50, 0x2000
	s_addc_u32 s51, s51, 0
	v_add_f32_dpp v236, v236, v236 row_half_mirror row_mask:0xf bank_mask:0xf
	s_nop 1
	v_add_f32_dpp v236, v236, v236 row_mirror row_mask:0xf bank_mask:0xf
	s_mov_b64 exec, s[48:49]
	global_store_dword v249, v236, s[34:35] offset:2048
	s_mov_b64 exec, -1
	s_waitcnt vmcnt(49) lgkmcnt(1)
	v_pk_add_f32 v[166:167], v[238:239], v[166:167]
	v_pk_add_f32 v[168:169], v[240:241], v[168:169]
	v_pk_mul_f32 v[242:243], v[166:167], v[166:167]
	v_pk_mul_f32 v[244:245], v[168:169], v[168:169]
	ds_read_b128 v[238:241], v237 offset:11264
	v_add_f32_e32 v246, v242, v243
	v_add_f32_e32 v246, v244, v246
	v_add_f32_e32 v246, v245, v246
	global_store_dwordx4 v247, v[166:169], s[38:39]
	v_cvt_pk_bf16_f32 v242, v166, v167
	v_cvt_pk_bf16_f32 v243, v168, v169
	v_add_f32_dpp v246, v246, v246 quad_perm:[1,0,3,2] row_mask:0xf bank_mask:0xf
	global_store_dwordx2 v248, v[242:243], s[50:51]
	s_add_u32 s38, s38, 0x4000
	s_addc_u32 s39, s39, 0
	v_add_f32_dpp v246, v246, v246 quad_perm:[2,3,0,1] row_mask:0xf bank_mask:0xf
	s_add_u32 s50, s50, 0x2000
	s_addc_u32 s51, s51, 0
	v_add_f32_dpp v246, v246, v246 row_half_mirror row_mask:0xf bank_mask:0xf
	s_nop 1
	v_add_f32_dpp v246, v246, v246 row_mirror row_mask:0xf bank_mask:0xf
	s_mov_b64 exec, s[48:49]
	global_store_dword v249, v246, s[34:35] offset:2304
	s_mov_b64 exec, -1
	s_waitcnt vmcnt(51) lgkmcnt(1)
	v_pk_add_f32 v[192:193], v[228:229], v[192:193]
	v_pk_add_f32 v[194:195], v[230:231], v[194:195]
	v_pk_mul_f32 v[232:233], v[192:193], v[192:193]
	v_pk_mul_f32 v[234:235], v[194:195], v[194:195]
	ds_read_b128 v[228:231], v210 offset:12288
	v_add_f32_e32 v236, v232, v233
	v_add_f32_e32 v236, v234, v236
	v_add_f32_e32 v236, v235, v236
	global_store_dwordx4 v247, v[192:195], s[38:39]
	v_cvt_pk_bf16_f32 v232, v192, v193
	v_cvt_pk_bf16_f32 v233, v194, v195
	v_add_f32_dpp v236, v236, v236 quad_perm:[1,0,3,2] row_mask:0xf bank_mask:0xf
	global_store_dwordx2 v248, v[232:233], s[50:51]
	s_add_u32 s38, s38, 0x4000
	s_addc_u32 s39, s39, 0
	v_add_f32_dpp v236, v236, v236 quad_perm:[2,3,0,1] row_mask:0xf bank_mask:0xf
	s_add_u32 s50, s50, 0x2000
	s_addc_u32 s51, s51, 0
	v_add_f32_dpp v236, v236, v236 row_half_mirror row_mask:0xf bank_mask:0xf
	s_nop 1
	v_add_f32_dpp v236, v236, v236 row_mirror row_mask:0xf bank_mask:0xf
	s_mov_b64 exec, s[48:49]
	global_store_dword v249, v236, s[34:35] offset:2560
	s_mov_b64 exec, -1
	s_waitcnt vmcnt(53) lgkmcnt(1)
	v_pk_add_f32 v[196:197], v[238:239], v[196:197]
	v_pk_add_f32 v[198:199], v[240:241], v[198:199]
	v_pk_mul_f32 v[242:243], v[196:197], v[196:197]
	v_pk_mul_f32 v[244:245], v[198:199], v[198:199]
	ds_read_b128 v[238:241], v211 offset:13312
	v_add_f32_e32 v246, v242, v243
	v_add_f32_e32 v246, v244, v246
	v_add_f32_e32 v246, v245, v246
	global_store_dwordx4 v247, v[196:199], s[38:39]
	v_cvt_pk_bf16_f32 v242, v196, v197
	v_cvt_pk_bf16_f32 v243, v198, v199
	v_add_f32_dpp v246, v246, v246 quad_perm:[1,0,3,2] row_mask:0xf bank_mask:0xf
	global_store_dwordx2 v248, v[242:243], s[50:51]
	s_add_u32 s38, s38, 0x4000
	s_addc_u32 s39, s39, 0
	v_add_f32_dpp v246, v246, v246 quad_perm:[2,3,0,1] row_mask:0xf bank_mask:0xf
	s_add_u32 s50, s50, 0x2000
	s_addc_u32 s51, s51, 0
	v_add_f32_dpp v246, v246, v246 row_half_mirror row_mask:0xf bank_mask:0xf
	s_nop 1
	v_add_f32_dpp v246, v246, v246 row_mirror row_mask:0xf bank_mask:0xf
	s_mov_b64 exec, s[48:49]
	global_store_dword v249, v246, s[34:35] offset:2816
	s_mov_b64 exec, -1
	s_waitcnt vmcnt(55) lgkmcnt(1)
	v_pk_add_f32 v[200:201], v[228:229], v[200:201]
	v_pk_add_f32 v[202:203], v[230:231], v[202:203]
	v_pk_mul_f32 v[232:233], v[200:201], v[200:201]
	v_pk_mul_f32 v[234:235], v[202:203], v[202:203]
	ds_read_b128 v[228:231], v215 offset:14336
	v_add_f32_e32 v236, v232, v233
	v_add_f32_e32 v236, v234, v236
	v_add_f32_e32 v236, v235, v236
	global_store_dwordx4 v247, v[200:203], s[38:39]
	v_cvt_pk_bf16_f32 v232, v200, v201
	v_cvt_pk_bf16_f32 v233, v202, v203
	v_add_f32_dpp v236, v236, v236 quad_perm:[1,0,3,2] row_mask:0xf bank_mask:0xf
	global_store_dwordx2 v248, v[232:233], s[50:51]
	s_add_u32 s38, s38, 0x4000
	s_addc_u32 s39, s39, 0
	v_add_f32_dpp v236, v236, v236 quad_perm:[2,3,0,1] row_mask:0xf bank_mask:0xf
	s_add_u32 s50, s50, 0x2000
	s_addc_u32 s51, s51, 0
	v_add_f32_dpp v236, v236, v236 row_half_mirror row_mask:0xf bank_mask:0xf
	s_nop 1
	v_add_f32_dpp v236, v236, v236 row_mirror row_mask:0xf bank_mask:0xf
	s_mov_b64 exec, s[48:49]
	global_store_dword v249, v236, s[34:35] offset:3072
	s_mov_b64 exec, -1
	s_waitcnt vmcnt(57) lgkmcnt(1)
	v_pk_add_f32 v[216:217], v[238:239], v[216:217]
	v_pk_add_f32 v[218:219], v[240:241], v[218:219]
	v_pk_mul_f32 v[242:243], v[216:217], v[216:217]
	v_pk_mul_f32 v[244:245], v[218:219], v[218:219]
	ds_read_b128 v[238:241], v237 offset:15360
	v_add_f32_e32 v246, v242, v243
	v_add_f32_e32 v246, v244, v246
	v_add_f32_e32 v246, v245, v246
	global_store_dwordx4 v247, v[216:219], s[38:39]
	v_cvt_pk_bf16_f32 v242, v216, v217
	v_cvt_pk_bf16_f32 v243, v218, v219
	v_add_f32_dpp v246, v246, v246 quad_perm:[1,0,3,2] row_mask:0xf bank_mask:0xf
	global_store_dwordx2 v248, v[242:243], s[50:51]
	s_add_u32 s38, s38, 0x4000
	s_addc_u32 s39, s39, 0
	v_add_f32_dpp v246, v246, v246 quad_perm:[2,3,0,1] row_mask:0xf bank_mask:0xf
	s_add_u32 s50, s50, 0x2000
	s_addc_u32 s51, s51, 0
	v_add_f32_dpp v246, v246, v246 row_half_mirror row_mask:0xf bank_mask:0xf
	s_nop 1
	v_add_f32_dpp v246, v246, v246 row_mirror row_mask:0xf bank_mask:0xf
	s_mov_b64 exec, s[48:49]
	global_store_dword v249, v246, s[34:35] offset:3328
	s_mov_b64 exec, -1
	s_waitcnt vmcnt(59) lgkmcnt(1)
	v_pk_add_f32 v[220:221], v[228:229], v[220:221]
	v_pk_add_f32 v[222:223], v[230:231], v[222:223]
	v_pk_mul_f32 v[232:233], v[220:221], v[220:221]
	v_pk_mul_f32 v[234:235], v[222:223], v[222:223]
	v_add_f32_e32 v236, v232, v233
	v_add_f32_e32 v236, v234, v236
	v_add_f32_e32 v236, v235, v236
	global_store_dwordx4 v247, v[220:223], s[38:39]
	v_cvt_pk_bf16_f32 v232, v220, v221
	v_cvt_pk_bf16_f32 v233, v222, v223
	v_add_f32_dpp v236, v236, v236 quad_perm:[1,0,3,2] row_mask:0xf bank_mask:0xf
	global_store_dwordx2 v248, v[232:233], s[50:51]
	s_add_u32 s38, s38, 0x4000
	s_addc_u32 s39, s39, 0
	v_add_f32_dpp v236, v236, v236 quad_perm:[2,3,0,1] row_mask:0xf bank_mask:0xf
	s_add_u32 s50, s50, 0x2000
	s_addc_u32 s51, s51, 0
	v_add_f32_dpp v236, v236, v236 row_half_mirror row_mask:0xf bank_mask:0xf
	s_nop 1
	v_add_f32_dpp v236, v236, v236 row_mirror row_mask:0xf bank_mask:0xf
	s_mov_b64 exec, s[48:49]
	global_store_dword v249, v236, s[34:35] offset:3584
	s_mov_b64 exec, -1
	s_waitcnt vmcnt(61) lgkmcnt(0)
	v_pk_add_f32 v[224:225], v[238:239], v[224:225]
	v_pk_add_f32 v[226:227], v[240:241], v[226:227]
	v_pk_mul_f32 v[242:243], v[224:225], v[224:225]
	v_pk_mul_f32 v[244:245], v[226:227], v[226:227]
	v_add_f32_e32 v246, v242, v243
	v_add_f32_e32 v246, v244, v246
	v_add_f32_e32 v246, v245, v246
	global_store_dwordx4 v247, v[224:227], s[38:39]
	v_cvt_pk_bf16_f32 v242, v224, v225
	v_cvt_pk_bf16_f32 v243, v226, v227
	v_add_f32_dpp v246, v246, v246 quad_perm:[1,0,3,2] row_mask:0xf bank_mask:0xf
	global_store_dwordx2 v248, v[242:243], s[50:51]
	s_add_u32 s38, s38, 0x4000
	s_addc_u32 s39, s39, 0
	v_add_f32_dpp v246, v246, v246 quad_perm:[2,3,0,1] row_mask:0xf bank_mask:0xf
	s_add_u32 s50, s50, 0x2000
	s_addc_u32 s51, s51, 0
	v_add_f32_dpp v246, v246, v246 row_half_mirror row_mask:0xf bank_mask:0xf
	s_nop 1
	v_add_f32_dpp v246, v246, v246 row_mirror row_mask:0xf bank_mask:0xf
	s_mov_b64 exec, s[48:49]
	global_store_dword v249, v246, s[34:35] offset:3840
	s_mov_b64 exec, -1
	s_add_u32 s34, s34, 0x1000
	s_addc_u32 s35, s35, 0
	v_and_b32_e32 v238, 15, v170
	v_xor_b32_e32 v238, v238, v171
	v_lshl_add_u32 v239, v170, 8, s40
	v_xor_b32_e32 v228, 0, v238
	v_lshl_add_u32 v228, v228, 4, v239
	v_xor_b32_e32 v229, 2, v238
	v_lshl_add_u32 v229, v229, 4, v239
	v_xor_b32_e32 v230, 4, v238
	v_lshl_add_u32 v230, v230, 4, v239
	v_xor_b32_e32 v231, 6, v238
	v_lshl_add_u32 v231, v231, 4, v239
	v_xor_b32_e32 v232, 8, v238
	v_lshl_add_u32 v232, v232, 4, v239
	v_xor_b32_e32 v233, 10, v238
	v_lshl_add_u32 v233, v233, 4, v239
	v_xor_b32_e32 v234, 12, v238
	v_lshl_add_u32 v234, v234, 4, v239
	v_xor_b32_e32 v235, 14, v238
	v_lshl_add_u32 v235, v235, 4, v239
	ds_write_b128 v228, v[18:21]
	ds_write_b128 v229, v[22:25]
	ds_write_b128 v230, v[26:29]
	ds_write_b128 v231, v[30:33]
	ds_write_b128 v232, v[50:53]
	ds_write_b128 v233, v[54:57]
	ds_write_b128 v234, v[58:61]
	ds_write_b128 v235, v[62:65]
	ds_write_b128 v228, v[2:5] offset:8192
	ds_write_b128 v229, v[6:9] offset:8192
	ds_write_b128 v230, v[10:13] offset:8192
	ds_write_b128 v231, v[14:17] offset:8192
	ds_write_b128 v232, v[34:37] offset:8192
	ds_write_b128 v233, v[38:41] offset:8192
	ds_write_b128 v234, v[42:45] offset:8192
	ds_write_b128 v235, v[46:49] offset:8192
	s_waitcnt lgkmcnt(0)
	ds_read_b128 v[228:231], v210 offset:0
	ds_read_b128 v[238:241], v211 offset:1024
	s_waitcnt vmcnt(63) lgkmcnt(1)
	v_pk_add_f32 v[66:67], v[228:229], v[66:67]
	v_pk_add_f32 v[68:69], v[230:231], v[68:69]
	v_pk_mul_f32 v[232:233], v[66:67], v[66:67]
	v_pk_mul_f32 v[234:235], v[68:69], v[68:69]
	ds_read_b128 v[228:231], v215 offset:2048
	v_add_f32_e32 v236, v232, v233
	v_add_f32_e32 v236, v234, v236
	v_add_f32_e32 v236, v235, v236
	global_store_dwordx4 v247, v[66:69], s[38:39]
	v_cvt_pk_bf16_f32 v232, v66, v67
	v_cvt_pk_bf16_f32 v233, v68, v69
	v_add_f32_dpp v236, v236, v236 quad_perm:[1,0,3,2] row_mask:0xf bank_mask:0xf
	global_store_dwordx2 v248, v[232:233], s[50:51]
	s_add_u32 s38, s38, 0x4000
	s_addc_u32 s39, s39, 0
	v_add_f32_dpp v236, v236, v236 quad_perm:[2,3,0,1] row_mask:0xf bank_mask:0xf
	s_add_u32 s50, s50, 0x2000
	s_addc_u32 s51, s51, 0
	v_add_f32_dpp v236, v236, v236 row_half_mirror row_mask:0xf bank_mask:0xf
	s_nop 1
	v_add_f32_dpp v236, v236, v236 row_mirror row_mask:0xf bank_mask:0xf
	s_mov_b64 exec, s[48:49]
	global_store_dword v249, v236, s[34:35] offset:0
	s_mov_b64 exec, -1
	s_waitcnt vmcnt(63) lgkmcnt(1)
	v_pk_add_f32 v[70:71], v[238:239], v[70:71]
	v_pk_add_f32 v[72:73], v[240:241], v[72:73]
	v_pk_mul_f32 v[242:243], v[70:71], v[70:71]
	v_pk_mul_f32 v[244:245], v[72:73], v[72:73]
	ds_read_b128 v[238:241], v237 offset:3072
	v_add_f32_e32 v246, v242, v243
	v_add_f32_e32 v246, v244, v246
	v_add_f32_e32 v246, v245, v246
	global_store_dwordx4 v247, v[70:73], s[38:39]
	v_cvt_pk_bf16_f32 v242, v70, v71
	v_cvt_pk_bf16_f32 v243, v72, v73
	v_add_f32_dpp v246, v246, v246 quad_perm:[1,0,3,2] row_mask:0xf bank_mask:0xf
	global_store_dwordx2 v248, v[242:243], s[50:51]
	s_add_u32 s38, s38, 0x4000
	s_addc_u32 s39, s39, 0
	v_add_f32_dpp v246, v246, v246 quad_perm:[2,3,0,1] row_mask:0xf bank_mask:0xf
	s_add_u32 s50, s50, 0x2000
	s_addc_u32 s51, s51, 0
	v_add_f32_dpp v246, v246, v246 row_half_mirror row_mask:0xf bank_mask:0xf
	s_nop 1
	v_add_f32_dpp v246, v246, v246 row_mirror row_mask:0xf bank_mask:0xf
	s_mov_b64 exec, s[48:49]
	global_store_dword v249, v246, s[34:35] offset:256
	s_mov_b64 exec, -1
	s_waitcnt vmcnt(63) lgkmcnt(1)
	v_pk_add_f32 v[74:75], v[228:229], v[74:75]
	v_pk_add_f32 v[76:77], v[230:231], v[76:77]
	v_pk_mul_f32 v[232:233], v[74:75], v[74:75]
	v_pk_mul_f32 v[234:235], v[76:77], v[76:77]
	ds_read_b128 v[228:231], v210 offset:4096
	v_add_f32_e32 v236, v232, v233
	v_add_f32_e32 v236, v234, v236
	v_add_f32_e32 v236, v235, v236
	global_store_dwordx4 v247, v[74:77], s[38:39]
	v_cvt_pk_bf16_f32 v232, v74, v75
	v_cvt_pk_bf16_f32 v233, v76, v77
	v_add_f32_dpp v236, v236, v236 quad_perm:[1,0,3,2] row_mask:0xf bank_mask:0xf
	global_store_dwordx2 v248, v[232:233], s[50:51]
	s_add_u32 s38, s38, 0x4000
	s_addc_u32 s39, s39, 0
	v_add_f32_dpp v236, v236, v236 quad_perm:[2,3,0,1] row_mask:0xf bank_mask:0xf
	s_add_u32 s50, s50, 0x2000
	s_addc_u32 s51, s51, 0
	v_add_f32_dpp v236, v236, v236 row_half_mirror row_mask:0xf bank_mask:0xf
	s_nop 1
	v_add_f32_dpp v236, v236, v236 row_mirror row_mask:0xf bank_mask:0xf
	s_mov_b64 exec, s[48:49]
	global_store_dword v249, v236, s[34:35] offset:512
	s_mov_b64 exec, -1
	s_waitcnt vmcnt(63) lgkmcnt(1)
	v_pk_add_f32 v[78:79], v[238:239], v[78:79]
	v_pk_add_f32 v[80:81], v[240:241], v[80:81]
	v_pk_mul_f32 v[242:243], v[78:79], v[78:79]
	v_pk_mul_f32 v[244:245], v[80:81], v[80:81]
	ds_read_b128 v[238:241], v211 offset:5120
	v_add_f32_e32 v246, v242, v243
	v_add_f32_e32 v246, v244, v246
	v_add_f32_e32 v246, v245, v246
	global_store_dwordx4 v247, v[78:81], s[38:39]
	v_cvt_pk_bf16_f32 v242, v78, v79
	v_cvt_pk_bf16_f32 v243, v80, v81
	v_add_f32_dpp v246, v246, v246 quad_perm:[1,0,3,2] row_mask:0xf bank_mask:0xf
	global_store_dwordx2 v248, v[242:243], s[50:51]
	s_add_u32 s38, s38, 0x4000
	s_addc_u32 s39, s39, 0
	v_add_f32_dpp v246, v246, v246 quad_perm:[2,3,0,1] row_mask:0xf bank_mask:0xf
	s_add_u32 s50, s50, 0x2000
	s_addc_u32 s51, s51, 0
	v_add_f32_dpp v246, v246, v246 row_half_mirror row_mask:0xf bank_mask:0xf
	s_nop 1
	v_add_f32_dpp v246, v246, v246 row_mirror row_mask:0xf bank_mask:0xf
	s_mov_b64 exec, s[48:49]
	global_store_dword v249, v246, s[34:35] offset:768
	s_mov_b64 exec, -1
	s_waitcnt vmcnt(63) lgkmcnt(1)
	v_pk_add_f32 v[114:115], v[228:229], v[114:115]
	v_pk_add_f32 v[116:117], v[230:231], v[116:117]
	v_pk_mul_f32 v[232:233], v[114:115], v[114:115]
	v_pk_mul_f32 v[234:235], v[116:117], v[116:117]
	ds_read_b128 v[228:231], v215 offset:6144
	v_add_f32_e32 v236, v232, v233
	v_add_f32_e32 v236, v234, v236
	v_add_f32_e32 v236, v235, v236
	global_store_dwordx4 v247, v[114:117], s[38:39]
	v_cvt_pk_bf16_f32 v232, v114, v115
	v_cvt_pk_bf16_f32 v233, v116, v117
	v_add_f32_dpp v236, v236, v236 quad_perm:[1,0,3,2] row_mask:0xf bank_mask:0xf
	global_store_dwordx2 v248, v[232:233], s[50:51]
	s_add_u32 s38, s38, 0x4000
	s_addc_u32 s39, s39, 0
	v_add_f32_dpp v236, v236, v236 quad_perm:[2,3,0,1] row_mask:0xf bank_mask:0xf
	s_add_u32 s50, s50, 0x2000
	s_addc_u32 s51, s51, 0
	v_add_f32_dpp v236, v236, v236 row_half_mirror row_mask:0xf bank_mask:0xf
	s_nop 1
	v_add_f32_dpp v236, v236, v236 row_mirror row_mask:0xf bank_mask:0xf
	s_mov_b64 exec, s[48:49]
	global_store_dword v249, v236, s[34:35] offset:1024
	s_mov_b64 exec, -1
	s_waitcnt vmcnt(63) lgkmcnt(1)
	v_pk_add_f32 v[118:119], v[238:239], v[118:119]
	v_pk_add_f32 v[120:121], v[240:241], v[120:121]
	v_pk_mul_f32 v[242:243], v[118:119], v[118:119]
	v_pk_mul_f32 v[244:245], v[120:121], v[120:121]
	ds_read_b128 v[238:241], v237 offset:7168
	v_add_f32_e32 v246, v242, v243
	v_add_f32_e32 v246, v244, v246
	v_add_f32_e32 v246, v245, v246
	global_store_dwordx4 v247, v[118:121], s[38:39]
	v_cvt_pk_bf16_f32 v242, v118, v119
	v_cvt_pk_bf16_f32 v243, v120, v121
	v_add_f32_dpp v246, v246, v246 quad_perm:[1,0,3,2] row_mask:0xf bank_mask:0xf
	global_store_dwordx2 v248, v[242:243], s[50:51]
	s_add_u32 s38, s38, 0x4000
	s_addc_u32 s39, s39, 0
	v_add_f32_dpp v246, v246, v246 quad_perm:[2,3,0,1] row_mask:0xf bank_mask:0xf
	s_add_u32 s50, s50, 0x2000
	s_addc_u32 s51, s51, 0
	v_add_f32_dpp v246, v246, v246 row_half_mirror row_mask:0xf bank_mask:0xf
	s_nop 1
	v_add_f32_dpp v246, v246, v246 row_mirror row_mask:0xf bank_mask:0xf
	s_mov_b64 exec, s[48:49]
	global_store_dword v249, v246, s[34:35] offset:1280
	s_mov_b64 exec, -1
	s_waitcnt vmcnt(63) lgkmcnt(1)
	v_pk_add_f32 v[122:123], v[228:229], v[122:123]
	v_pk_add_f32 v[124:125], v[230:231], v[124:125]
	v_pk_mul_f32 v[232:233], v[122:123], v[122:123]
	v_pk_mul_f32 v[234:235], v[124:125], v[124:125]
	ds_read_b128 v[228:231], v210 offset:8192
	v_add_f32_e32 v236, v232, v233
	v_add_f32_e32 v236, v234, v236
	v_add_f32_e32 v236, v235, v236
	global_store_dwordx4 v247, v[122:125], s[38:39]
	v_cvt_pk_bf16_f32 v232, v122, v123
	v_cvt_pk_bf16_f32 v233, v124, v125
	v_add_f32_dpp v236, v236, v236 quad_perm:[1,0,3,2] row_mask:0xf bank_mask:0xf
	global_store_dwordx2 v248, v[232:233], s[50:51]
	s_add_u32 s38, s38, 0x4000
	s_addc_u32 s39, s39, 0
	v_add_f32_dpp v236, v236, v236 quad_perm:[2,3,0,1] row_mask:0xf bank_mask:0xf
	s_add_u32 s50, s50, 0x2000
	s_addc_u32 s51, s51, 0
	v_add_f32_dpp v236, v236, v236 row_half_mirror row_mask:0xf bank_mask:0xf
	s_nop 1
	v_add_f32_dpp v236, v236, v236 row_mirror row_mask:0xf bank_mask:0xf
	s_mov_b64 exec, s[48:49]
	global_store_dword v249, v236, s[34:35] offset:1536
	s_mov_b64 exec, -1
	s_waitcnt vmcnt(63) lgkmcnt(1)
	v_pk_add_f32 v[126:127], v[238:239], v[126:127]
	v_pk_add_f32 v[128:129], v[240:241], v[128:129]
	v_pk_mul_f32 v[242:243], v[126:127], v[126:127]
	v_pk_mul_f32 v[244:245], v[128:129], v[128:129]
	ds_read_b128 v[238:241], v211 offset:9216
	v_add_f32_e32 v246, v242, v243
	v_add_f32_e32 v246, v244, v246
	v_add_f32_e32 v246, v245, v246
	global_store_dwordx4 v247, v[126:129], s[38:39]
	v_cvt_pk_bf16_f32 v242, v126, v127
	v_cvt_pk_bf16_f32 v243, v128, v129
	v_add_f32_dpp v246, v246, v246 quad_perm:[1,0,3,2] row_mask:0xf bank_mask:0xf
	global_store_dwordx2 v248, v[242:243], s[50:51]
	s_add_u32 s38, s38, 0x4000
	s_addc_u32 s39, s39, 0
	v_add_f32_dpp v246, v246, v246 quad_perm:[2,3,0,1] row_mask:0xf bank_mask:0xf
	s_add_u32 s50, s50, 0x2000
	s_addc_u32 s51, s51, 0
	v_add_f32_dpp v246, v246, v246 row_half_mirror row_mask:0xf bank_mask:0xf
	s_nop 1
	v_add_f32_dpp v246, v246, v246 row_mirror row_mask:0xf bank_mask:0xf
	s_mov_b64 exec, s[48:49]
	global_store_dword v249, v246, s[34:35] offset:1792
	s_mov_b64 exec, -1
	s_waitcnt vmcnt(63) lgkmcnt(1)
	v_pk_add_f32 v[82:83], v[228:229], v[82:83]
	v_pk_add_f32 v[84:85], v[230:231], v[84:85]
	v_pk_mul_f32 v[232:233], v[82:83], v[82:83]
	v_pk_mul_f32 v[234:235], v[84:85], v[84:85]
	ds_read_b128 v[228:231], v215 offset:10240
	v_add_f32_e32 v236, v232, v233
	v_add_f32_e32 v236, v234, v236
	v_add_f32_e32 v236, v235, v236
	global_store_dwordx4 v247, v[82:85], s[38:39]
	v_cvt_pk_bf16_f32 v232, v82, v83
	v_cvt_pk_bf16_f32 v233, v84, v85
	v_add_f32_dpp v236, v236, v236 quad_perm:[1,0,3,2] row_mask:0xf bank_mask:0xf
	global_store_dwordx2 v248, v[232:233], s[50:51]
	s_add_u32 s38, s38, 0x4000
	s_addc_u32 s39, s39, 0
	v_add_f32_dpp v236, v236, v236 quad_perm:[2,3,0,1] row_mask:0xf bank_mask:0xf
	s_add_u32 s50, s50, 0x2000
	s_addc_u32 s51, s51, 0
	v_add_f32_dpp v236, v236, v236 row_half_mirror row_mask:0xf bank_mask:0xf
	s_nop 1
	v_add_f32_dpp v236, v236, v236 row_mirror row_mask:0xf bank_mask:0xf
	s_mov_b64 exec, s[48:49]
	global_store_dword v249, v236, s[34:35] offset:2048
	s_mov_b64 exec, -1
	s_waitcnt vmcnt(63) lgkmcnt(1)
	v_pk_add_f32 v[86:87], v[238:239], v[86:87]
	v_pk_add_f32 v[88:89], v[240:241], v[88:89]
	v_pk_mul_f32 v[242:243], v[86:87], v[86:87]
	v_pk_mul_f32 v[244:245], v[88:89], v[88:89]
	ds_read_b128 v[238:241], v237 offset:11264
	v_add_f32_e32 v246, v242, v243
	v_add_f32_e32 v246, v244, v246
	v_add_f32_e32 v246, v245, v246
	global_store_dwordx4 v247, v[86:89], s[38:39]
	v_cvt_pk_bf16_f32 v242, v86, v87
	v_cvt_pk_bf16_f32 v243, v88, v89
	v_add_f32_dpp v246, v246, v246 quad_perm:[1,0,3,2] row_mask:0xf bank_mask:0xf
	global_store_dwordx2 v248, v[242:243], s[50:51]
	s_add_u32 s38, s38, 0x4000
	s_addc_u32 s39, s39, 0
	v_add_f32_dpp v246, v246, v246 quad_perm:[2,3,0,1] row_mask:0xf bank_mask:0xf
	s_add_u32 s50, s50, 0x2000
	s_addc_u32 s51, s51, 0
	v_add_f32_dpp v246, v246, v246 row_half_mirror row_mask:0xf bank_mask:0xf
	s_nop 1
	v_add_f32_dpp v246, v246, v246 row_mirror row_mask:0xf bank_mask:0xf
	s_mov_b64 exec, s[48:49]
	global_store_dword v249, v246, s[34:35] offset:2304
	s_mov_b64 exec, -1
	s_waitcnt vmcnt(63) lgkmcnt(1)
	v_pk_add_f32 v[90:91], v[228:229], v[90:91]
	v_pk_add_f32 v[92:93], v[230:231], v[92:93]
	v_pk_mul_f32 v[232:233], v[90:91], v[90:91]
	v_pk_mul_f32 v[234:235], v[92:93], v[92:93]
	ds_read_b128 v[228:231], v210 offset:12288
	v_add_f32_e32 v236, v232, v233
	v_add_f32_e32 v236, v234, v236
	v_add_f32_e32 v236, v235, v236
	global_store_dwordx4 v247, v[90:93], s[38:39]
	v_cvt_pk_bf16_f32 v232, v90, v91
	v_cvt_pk_bf16_f32 v233, v92, v93
	v_add_f32_dpp v236, v236, v236 quad_perm:[1,0,3,2] row_mask:0xf bank_mask:0xf
	global_store_dwordx2 v248, v[232:233], s[50:51]
	s_add_u32 s38, s38, 0x4000
	s_addc_u32 s39, s39, 0
	v_add_f32_dpp v236, v236, v236 quad_perm:[2,3,0,1] row_mask:0xf bank_mask:0xf
	s_add_u32 s50, s50, 0x2000
	s_addc_u32 s51, s51, 0
	v_add_f32_dpp v236, v236, v236 row_half_mirror row_mask:0xf bank_mask:0xf
	s_nop 1
	v_add_f32_dpp v236, v236, v236 row_mirror row_mask:0xf bank_mask:0xf
	s_mov_b64 exec, s[48:49]
	global_store_dword v249, v236, s[34:35] offset:2560
	s_mov_b64 exec, -1
	s_waitcnt vmcnt(63) lgkmcnt(1)
	v_pk_add_f32 v[94:95], v[238:239], v[94:95]
	v_pk_add_f32 v[96:97], v[240:241], v[96:97]
	v_pk_mul_f32 v[242:243], v[94:95], v[94:95]
	v_pk_mul_f32 v[244:245], v[96:97], v[96:97]
	ds_read_b128 v[238:241], v211 offset:13312
	v_add_f32_e32 v246, v242, v243
	v_add_f32_e32 v246, v244, v246
	v_add_f32_e32 v246, v245, v246
	global_store_dwordx4 v247, v[94:97], s[38:39]
	v_cvt_pk_bf16_f32 v242, v94, v95
	v_cvt_pk_bf16_f32 v243, v96, v97
	v_add_f32_dpp v246, v246, v246 quad_perm:[1,0,3,2] row_mask:0xf bank_mask:0xf
	global_store_dwordx2 v248, v[242:243], s[50:51]
	s_add_u32 s38, s38, 0x4000
	s_addc_u32 s39, s39, 0
	v_add_f32_dpp v246, v246, v246 quad_perm:[2,3,0,1] row_mask:0xf bank_mask:0xf
	s_add_u32 s50, s50, 0x2000
	s_addc_u32 s51, s51, 0
	v_add_f32_dpp v246, v246, v246 row_half_mirror row_mask:0xf bank_mask:0xf
	s_nop 1
	v_add_f32_dpp v246, v246, v246 row_mirror row_mask:0xf bank_mask:0xf
	s_mov_b64 exec, s[48:49]
	global_store_dword v249, v246, s[34:35] offset:2816
	s_mov_b64 exec, -1
	s_waitcnt vmcnt(63) lgkmcnt(1)
	v_pk_add_f32 v[98:99], v[228:229], v[98:99]
	v_pk_add_f32 v[100:101], v[230:231], v[100:101]
	v_pk_mul_f32 v[232:233], v[98:99], v[98:99]
	v_pk_mul_f32 v[234:235], v[100:101], v[100:101]
	ds_read_b128 v[228:231], v215 offset:14336
	v_add_f32_e32 v236, v232, v233
	v_add_f32_e32 v236, v234, v236
	v_add_f32_e32 v236, v235, v236
	global_store_dwordx4 v247, v[98:101], s[38:39]
	v_cvt_pk_bf16_f32 v232, v98, v99
	v_cvt_pk_bf16_f32 v233, v100, v101
	v_add_f32_dpp v236, v236, v236 quad_perm:[1,0,3,2] row_mask:0xf bank_mask:0xf
	global_store_dwordx2 v248, v[232:233], s[50:51]
	s_add_u32 s38, s38, 0x4000
	s_addc_u32 s39, s39, 0
	v_add_f32_dpp v236, v236, v236 quad_perm:[2,3,0,1] row_mask:0xf bank_mask:0xf
	s_add_u32 s50, s50, 0x2000
	s_addc_u32 s51, s51, 0
	v_add_f32_dpp v236, v236, v236 row_half_mirror row_mask:0xf bank_mask:0xf
	s_nop 1
	v_add_f32_dpp v236, v236, v236 row_mirror row_mask:0xf bank_mask:0xf
	s_mov_b64 exec, s[48:49]
	global_store_dword v249, v236, s[34:35] offset:3072
	s_mov_b64 exec, -1
	s_waitcnt vmcnt(63) lgkmcnt(1)
	v_pk_add_f32 v[102:103], v[238:239], v[102:103]
	v_pk_add_f32 v[104:105], v[240:241], v[104:105]
	v_pk_mul_f32 v[242:243], v[102:103], v[102:103]
	v_pk_mul_f32 v[244:245], v[104:105], v[104:105]
	ds_read_b128 v[238:241], v237 offset:15360
	v_add_f32_e32 v246, v242, v243
	v_add_f32_e32 v246, v244, v246
	v_add_f32_e32 v246, v245, v246
	global_store_dwordx4 v247, v[102:105], s[38:39]
	v_cvt_pk_bf16_f32 v242, v102, v103
	v_cvt_pk_bf16_f32 v243, v104, v105
	v_add_f32_dpp v246, v246, v246 quad_perm:[1,0,3,2] row_mask:0xf bank_mask:0xf
	global_store_dwordx2 v248, v[242:243], s[50:51]
	s_add_u32 s38, s38, 0x4000
	s_addc_u32 s39, s39, 0
	v_add_f32_dpp v246, v246, v246 quad_perm:[2,3,0,1] row_mask:0xf bank_mask:0xf
	s_add_u32 s50, s50, 0x2000
	s_addc_u32 s51, s51, 0
	v_add_f32_dpp v246, v246, v246 row_half_mirror row_mask:0xf bank_mask:0xf
	s_nop 1
	v_add_f32_dpp v246, v246, v246 row_mirror row_mask:0xf bank_mask:0xf
	s_mov_b64 exec, s[48:49]
	global_store_dword v249, v246, s[34:35] offset:3328
	s_mov_b64 exec, -1
	s_waitcnt vmcnt(63) lgkmcnt(1)
	v_pk_add_f32 v[106:107], v[228:229], v[106:107]
	v_pk_add_f32 v[108:109], v[230:231], v[108:109]
	v_pk_mul_f32 v[232:233], v[106:107], v[106:107]
	v_pk_mul_f32 v[234:235], v[108:109], v[108:109]
	v_add_f32_e32 v236, v232, v233
	v_add_f32_e32 v236, v234, v236
	v_add_f32_e32 v236, v235, v236
	global_store_dwordx4 v247, v[106:109], s[38:39]
	v_cvt_pk_bf16_f32 v232, v106, v107
	v_cvt_pk_bf16_f32 v233, v108, v109
	v_add_f32_dpp v236, v236, v236 quad_perm:[1,0,3,2] row_mask:0xf bank_mask:0xf
	global_store_dwordx2 v248, v[232:233], s[50:51]
	s_add_u32 s38, s38, 0x4000
	s_addc_u32 s39, s39, 0
	v_add_f32_dpp v236, v236, v236 quad_perm:[2,3,0,1] row_mask:0xf bank_mask:0xf
	s_add_u32 s50, s50, 0x2000
	s_addc_u32 s51, s51, 0
	v_add_f32_dpp v236, v236, v236 row_half_mirror row_mask:0xf bank_mask:0xf
	s_nop 1
	v_add_f32_dpp v236, v236, v236 row_mirror row_mask:0xf bank_mask:0xf
	s_mov_b64 exec, s[48:49]
	global_store_dword v249, v236, s[34:35] offset:3584
	s_mov_b64 exec, -1
	s_waitcnt vmcnt(63) lgkmcnt(0)
	v_pk_add_f32 v[110:111], v[238:239], v[110:111]
	v_pk_add_f32 v[112:113], v[240:241], v[112:113]
	v_pk_mul_f32 v[242:243], v[110:111], v[110:111]
	v_pk_mul_f32 v[244:245], v[112:113], v[112:113]
	v_add_f32_e32 v246, v242, v243
	v_add_f32_e32 v246, v244, v246
	v_add_f32_e32 v246, v245, v246
	global_store_dwordx4 v247, v[110:113], s[38:39]
	v_cvt_pk_bf16_f32 v242, v110, v111
	v_cvt_pk_bf16_f32 v243, v112, v113
	v_add_f32_dpp v246, v246, v246 quad_perm:[1,0,3,2] row_mask:0xf bank_mask:0xf
	global_store_dwordx2 v248, v[242:243], s[50:51]
	s_add_u32 s38, s38, 0x4000
	s_addc_u32 s39, s39, 0
	v_add_f32_dpp v246, v246, v246 quad_perm:[2,3,0,1] row_mask:0xf bank_mask:0xf
	s_add_u32 s50, s50, 0x2000
	s_addc_u32 s51, s51, 0
	v_add_f32_dpp v246, v246, v246 row_half_mirror row_mask:0xf bank_mask:0xf
	s_nop 1
	v_add_f32_dpp v246, v246, v246 row_mirror row_mask:0xf bank_mask:0xf
	s_mov_b64 exec, s[48:49]
	global_store_dword v249, v246, s[34:35] offset:3840
	s_mov_b64 exec, -1
	s_waitcnt lgkmcnt(0)
	s_branch .LBB0_1677

.Lres_mlp2_l0:
	v_readfirstlane_b32 s40, v204
	s_lshr_b32 s40, s40, 6
	s_and_b32 s41, s40, 1
	s_bfe_u32 s42, s40, 0x10001
	s_lshr_b32 s43, s40, 2
	s_lshl_b32 s44, s4, 1
	s_add_i32 s44, s44, s42
	s_lshl_b32 s45, s44, 7
	s_lshl_b32 s46, s41, 6
	s_add_i32 s45, s45, s46
	s_lshl_b32 s46, s43, 7
	s_add_i32 s46, s46, s2
	s_lshl_b32 s47, s44, 1
	s_add_i32 s47, s47, s41
	v_readlane_b32 s36, v250, 9
	v_readlane_b32 s37, v250, 10
	s_mov_b64 s[38:39], s[36:37]
	v_readlane_b32 s50, v250, 11
	v_readlane_b32 s51, v250, 12
	s_add_u32 s34, s50, 0xf900000
	s_addc_u32 s35, s51, 0
	s_add_u32 s50, s50, 0x5800000
	s_addc_u32 s51, s51, 0
	s_lshl_b32 s48, s46, 12
	s_lshl_b32 s49, s45, 2
	s_add_u32 s48, s48, s49
	s_add_u32 s36, s36, s48
	s_addc_u32 s37, s37, 0
	s_add_u32 s38, s38, s48
	s_addc_u32 s39, s39, 0
	s_lshr_b32 s48, s48, 1
	s_add_u32 s50, s50, s48
	s_addc_u32 s51, s51, 0
	s_lshl_b32 s48, s46, 6
	s_lshl_b32 s49, s47, 2
	s_add_u32 s48, s48, s49
	s_add_u32 s34, s34, s48
	s_addc_u32 s35, s35, 0
	v_and_b32_e32 v249, 63, v204
	v_and_b32_e32 v170, 31, v249
	v_lshrrev_b32_e32 v171, 5, v249
	v_and_b32_e32 v208, 15, v249
	v_lshrrev_b32_e32 v209, 4, v249
	s_lshl_b32 s40, s40, 14
	v_and_b32_e32 v238, 15, v170
	v_xor_b32_e32 v238, v238, v171
	v_lshl_add_u32 v239, v170, 8, s40
	v_xor_b32_e32 v228, 0, v238
	v_lshl_add_u32 v228, v228, 4, v239
	v_xor_b32_e32 v229, 2, v238
	v_lshl_add_u32 v229, v229, 4, v239
	v_xor_b32_e32 v230, 4, v238
	v_lshl_add_u32 v230, v230, 4, v239
	v_xor_b32_e32 v231, 6, v238
	v_lshl_add_u32 v231, v231, 4, v239
	v_xor_b32_e32 v232, 8, v238
	v_lshl_add_u32 v232, v232, 4, v239
	v_xor_b32_e32 v233, 10, v238
	v_lshl_add_u32 v233, v233, 4, v239
	v_xor_b32_e32 v234, 12, v238
	v_lshl_add_u32 v234, v234, 4, v239
	v_xor_b32_e32 v235, 14, v238
	v_lshl_add_u32 v235, v235, 4, v239
	v_lshl_add_u32 v239, v209, 8, s40
	v_add_u32_e32 v210, 0, v209
	v_xor_b32_e32 v210, v210, v208
	v_lshl_add_u32 v210, v210, 4, v239
	v_add_u32_e32 v211, 4, v209
	v_xor_b32_e32 v211, v211, v208
	v_lshl_add_u32 v211, v211, 4, v239
	v_add_u32_e32 v215, 8, v209
	v_xor_b32_e32 v215, v215, v208
	v_lshl_add_u32 v215, v215, 4, v239
	v_add_u32_e32 v237, 12, v209
	v_xor_b32_e32 v237, v237, v208
	v_lshl_add_u32 v237, v237, 4, v239
	v_lshlrev_b32_e32 v247, 12, v209
	v_lshl_add_u32 v247, v208, 4, v247
	v_lshrrev_b32_e32 v248, 1, v247
	v_lshlrev_b32_e32 v249, 6, v209
	s_mov_b32 s48, 0x00010001
	s_mov_b32 s49, 0x00010001
	global_load_dwordx4 v[130:133], v247, s[36:37]
	s_add_u32 s36, s36, 0x4000
	s_addc_u32 s37, s37, 0
	global_load_dwordx4 v[134:137], v247, s[36:37]
	s_add_u32 s36, s36, 0x4000
	s_addc_u32 s37, s37, 0
	global_load_dwordx4 v[138:141], v247, s[36:37]
	s_add_u32 s36, s36, 0x4000
	s_addc_u32 s37, s37, 0
	global_load_dwordx4 v[142:145], v247, s[36:37]
	s_add_u32 s36, s36, 0x4000
	s_addc_u32 s37, s37, 0
	global_load_dwordx4 v[146:149], v247, s[36:37]
	s_add_u32 s36, s36, 0x4000
	s_addc_u32 s37, s37, 0
	global_load_dwordx4 v[150:153], v247, s[36:37]
	s_add_u32 s36, s36, 0x4000
	s_addc_u32 s37, s37, 0
	global_load_dwordx4 v[154:157], v247, s[36:37]
	s_add_u32 s36, s36, 0x4000
	s_addc_u32 s37, s37, 0
	global_load_dwordx4 v[158:161], v247, s[36:37]
	s_add_u32 s36, s36, 0x4000
	s_addc_u32 s37, s37, 0
	global_load_dwordx4 v[162:165], v247, s[36:37]
	s_add_u32 s36, s36, 0x4000
	s_addc_u32 s37, s37, 0
	global_load_dwordx4 v[166:169], v247, s[36:37]
	s_add_u32 s36, s36, 0x4000
	s_addc_u32 s37, s37, 0
	global_load_dwordx4 v[192:195], v247, s[36:37]
	s_add_u32 s36, s36, 0x4000
	s_addc_u32 s37, s37, 0
	global_load_dwordx4 v[196:199], v247, s[36:37]
	s_add_u32 s36, s36, 0x4000
	s_addc_u32 s37, s37, 0
	global_load_dwordx4 v[200:203], v247, s[36:37]
	s_add_u32 s36, s36, 0x4000
	s_addc_u32 s37, s37, 0
	global_load_dwordx4 v[216:219], v247, s[36:37]
	s_add_u32 s36, s36, 0x4000
	s_addc_u32 s37, s37, 0
	global_load_dwordx4 v[220:223], v247, s[36:37]
	s_add_u32 s36, s36, 0x4000
	s_addc_u32 s37, s37, 0
	global_load_dwordx4 v[224:227], v247, s[36:37]
	s_add_u32 s36, s36, 0x4000
	s_addc_u32 s37, s37, 0
	ds_write_b128 v228, v[66:69]
	ds_write_b128 v229, v[70:73]
	ds_write_b128 v230, v[74:77]
	ds_write_b128 v231, v[78:81]
	ds_write_b128 v232, v[114:117]
	ds_write_b128 v233, v[118:121]
	ds_write_b128 v234, v[122:125]
	ds_write_b128 v235, v[126:129]
	ds_write_b128 v228, v[82:85] offset:8192
	ds_write_b128 v229, v[86:89] offset:8192
	ds_write_b128 v230, v[90:93] offset:8192
	ds_write_b128 v231, v[94:97] offset:8192
	ds_write_b128 v232, v[98:101] offset:8192
	ds_write_b128 v233, v[102:105] offset:8192
	ds_write_b128 v234, v[106:109] offset:8192
	ds_write_b128 v235, v[110:113] offset:8192
	global_load_dwordx4 v[66:69], v247, s[36:37]
	s_add_u32 s36, s36, 0x4000
	s_addc_u32 s37, s37, 0
	global_load_dwordx4 v[70:73], v247, s[36:37]
	s_add_u32 s36, s36, 0x4000
	s_addc_u32 s37, s37, 0
	global_load_dwordx4 v[74:77], v247, s[36:37]
	s_add_u32 s36, s36, 0x4000
	s_addc_u32 s37, s37, 0
	global_load_dwordx4 v[78:81], v247, s[36:37]
	s_add_u32 s36, s36, 0x4000
	s_addc_u32 s37, s37, 0
	global_load_dwordx4 v[114:117], v247, s[36:37]
	s_add_u32 s36, s36, 0x4000
	s_addc_u32 s37, s37, 0
	global_load_dwordx4 v[118:121], v247, s[36:37]
	s_add_u32 s36, s36, 0x4000
	s_addc_u32 s37, s37, 0
	global_load_dwordx4 v[122:125], v247, s[36:37]
	s_add_u32 s36, s36, 0x4000
	s_addc_u32 s37, s37, 0
	global_load_dwordx4 v[126:129], v247, s[36:37]
	s_add_u32 s36, s36, 0x4000
	s_addc_u32 s37, s37, 0
	global_load_dwordx4 v[82:85], v247, s[36:37]
	s_add_u32 s36, s36, 0x4000
	s_addc_u32 s37, s37, 0
	global_load_dwordx4 v[86:89], v247, s[36:37]
	s_add_u32 s36, s36, 0x4000
	s_addc_u32 s37, s37, 0
	global_load_dwordx4 v[90:93], v247, s[36:37]
	s_add_u32 s36, s36, 0x4000
	s_addc_u32 s37, s37, 0
	global_load_dwordx4 v[94:97], v247, s[36:37]
	s_add_u32 s36, s36, 0x4000
	s_addc_u32 s37, s37, 0
	global_load_dwordx4 v[98:101], v247, s[36:37]
	s_add_u32 s36, s36, 0x4000
	s_addc_u32 s37, s37, 0
	global_load_dwordx4 v[102:105], v247, s[36:37]
	s_add_u32 s36, s36, 0x4000
	s_addc_u32 s37, s37, 0
	global_load_dwordx4 v[106:109], v247, s[36:37]
	s_add_u32 s36, s36, 0x4000
	s_addc_u32 s37, s37, 0
	global_load_dwordx4 v[110:113], v247, s[36:37]
	s_add_u32 s36, s36, 0x4000
	s_addc_u32 s37, s37, 0
	s_waitcnt lgkmcnt(0)
	ds_read_b128 v[228:231], v210 offset:0
	ds_read_b128 v[238:241], v211 offset:1024
	s_waitcnt vmcnt(31) lgkmcnt(1)
	v_pk_add_f32 v[130:131], v[228:229], v[130:131]
	v_pk_add_f32 v[132:133], v[230:231], v[132:133]
	v_pk_mul_f32 v[232:233], v[130:131], v[130:131]
	v_pk_mul_f32 v[234:235], v[132:133], v[132:133]
	ds_read_b128 v[228:231], v215 offset:2048
	v_add_f32_e32 v236, v232, v233
	v_add_f32_e32 v236, v234, v236
	v_add_f32_e32 v236, v235, v236
	global_store_dwordx4 v247, v[130:133], s[38:39]
	v_add_f32_dpp v236, v236, v236 quad_perm:[1,0,3,2] row_mask:0xf bank_mask:0xf
	s_add_u32 s38, s38, 0x4000
	s_addc_u32 s39, s39, 0
	v_add_f32_dpp v236, v236, v236 quad_perm:[2,3,0,1] row_mask:0xf bank_mask:0xf
	s_nop 1
	v_add_f32_dpp v236, v236, v236 row_half_mirror row_mask:0xf bank_mask:0xf
	s_nop 1
	v_add_f32_dpp v236, v236, v236 row_mirror row_mask:0xf bank_mask:0xf
	s_mov_b64 exec, s[48:49]
	global_store_dword v249, v236, s[34:35] offset:0
	s_mov_b64 exec, -1
	s_waitcnt vmcnt(32) lgkmcnt(1)
	v_pk_add_f32 v[134:135], v[238:239], v[134:135]
	v_pk_add_f32 v[136:137], v[240:241], v[136:137]
	v_pk_mul_f32 v[242:243], v[134:135], v[134:135]
	v_pk_mul_f32 v[244:245], v[136:137], v[136:137]
	ds_read_b128 v[238:241], v237 offset:3072
	v_add_f32_e32 v246, v242, v243
	v_add_f32_e32 v246, v244, v246
	v_add_f32_e32 v246, v245, v246
	global_store_dwordx4 v247, v[134:137], s[38:39]
	v_add_f32_dpp v246, v246, v246 quad_perm:[1,0,3,2] row_mask:0xf bank_mask:0xf
	s_add_u32 s38, s38, 0x4000
	s_addc_u32 s39, s39, 0
	v_add_f32_dpp v246, v246, v246 quad_perm:[2,3,0,1] row_mask:0xf bank_mask:0xf
	s_nop 1
	v_add_f32_dpp v246, v246, v246 row_half_mirror row_mask:0xf bank_mask:0xf
	s_nop 1
	v_add_f32_dpp v246, v246, v246 row_mirror row_mask:0xf bank_mask:0xf
	s_mov_b64 exec, s[48:49]
	global_store_dword v249, v246, s[34:35] offset:256
	s_mov_b64 exec, -1
	s_waitcnt vmcnt(33) lgkmcnt(1)
	v_pk_add_f32 v[138:139], v[228:229], v[138:139]
	v_pk_add_f32 v[140:141], v[230:231], v[140:141]
	v_pk_mul_f32 v[232:233], v[138:139], v[138:139]
	v_pk_mul_f32 v[234:235], v[140:141], v[140:141]
	ds_read_b128 v[228:231], v210 offset:4096
	v_add_f32_e32 v236, v232, v233
	v_add_f32_e32 v236, v234, v236
	v_add_f32_e32 v236, v235, v236
	global_store_dwordx4 v247, v[138:141], s[38:39]
	v_add_f32_dpp v236, v236, v236 quad_perm:[1,0,3,2] row_mask:0xf bank_mask:0xf
	s_add_u32 s38, s38, 0x4000
	s_addc_u32 s39, s39, 0
	v_add_f32_dpp v236, v236, v236 quad_perm:[2,3,0,1] row_mask:0xf bank_mask:0xf
	s_nop 1
	v_add_f32_dpp v236, v236, v236 row_half_mirror row_mask:0xf bank_mask:0xf
	s_nop 1
	v_add_f32_dpp v236, v236, v236 row_mirror row_mask:0xf bank_mask:0xf
	s_mov_b64 exec, s[48:49]
	global_store_dword v249, v236, s[34:35] offset:512
	s_mov_b64 exec, -1
	s_waitcnt vmcnt(34) lgkmcnt(1)
	v_pk_add_f32 v[142:143], v[238:239], v[142:143]
	v_pk_add_f32 v[144:145], v[240:241], v[144:145]
	v_pk_mul_f32 v[242:243], v[142:143], v[142:143]
	v_pk_mul_f32 v[244:245], v[144:145], v[144:145]
	ds_read_b128 v[238:241], v211 offset:5120
	v_add_f32_e32 v246, v242, v243
	v_add_f32_e32 v246, v244, v246
	v_add_f32_e32 v246, v245, v246
	global_store_dwordx4 v247, v[142:145], s[38:39]
	v_add_f32_dpp v246, v246, v246 quad_perm:[1,0,3,2] row_mask:0xf bank_mask:0xf
	s_add_u32 s38, s38, 0x4000
	s_addc_u32 s39, s39, 0
	v_add_f32_dpp v246, v246, v246 quad_perm:[2,3,0,1] row_mask:0xf bank_mask:0xf
	s_nop 1
	v_add_f32_dpp v246, v246, v246 row_half_mirror row_mask:0xf bank_mask:0xf
	s_nop 1
	v_add_f32_dpp v246, v246, v246 row_mirror row_mask:0xf bank_mask:0xf
	s_mov_b64 exec, s[48:49]
	global_store_dword v249, v246, s[34:35] offset:768
	s_mov_b64 exec, -1
	s_waitcnt vmcnt(35) lgkmcnt(1)
	v_pk_add_f32 v[146:147], v[228:229], v[146:147]
	v_pk_add_f32 v[148:149], v[230:231], v[148:149]
	v_pk_mul_f32 v[232:233], v[146:147], v[146:147]
	v_pk_mul_f32 v[234:235], v[148:149], v[148:149]
	ds_read_b128 v[228:231], v215 offset:6144
	v_add_f32_e32 v236, v232, v233
	v_add_f32_e32 v236, v234, v236
	v_add_f32_e32 v236, v235, v236
	global_store_dwordx4 v247, v[146:149], s[38:39]
	v_add_f32_dpp v236, v236, v236 quad_perm:[1,0,3,2] row_mask:0xf bank_mask:0xf
	s_add_u32 s38, s38, 0x4000
	s_addc_u32 s39, s39, 0
	v_add_f32_dpp v236, v236, v236 quad_perm:[2,3,0,1] row_mask:0xf bank_mask:0xf
	s_nop 1
	v_add_f32_dpp v236, v236, v236 row_half_mirror row_mask:0xf bank_mask:0xf
	s_nop 1
	v_add_f32_dpp v236, v236, v236 row_mirror row_mask:0xf bank_mask:0xf
	s_mov_b64 exec, s[48:49]
	global_store_dword v249, v236, s[34:35] offset:1024
	s_mov_b64 exec, -1
	s_waitcnt vmcnt(36) lgkmcnt(1)
	v_pk_add_f32 v[150:151], v[238:239], v[150:151]
	v_pk_add_f32 v[152:153], v[240:241], v[152:153]
	v_pk_mul_f32 v[242:243], v[150:151], v[150:151]
	v_pk_mul_f32 v[244:245], v[152:153], v[152:153]
	ds_read_b128 v[238:241], v237 offset:7168
	v_add_f32_e32 v246, v242, v243
	v_add_f32_e32 v246, v244, v246
	v_add_f32_e32 v246, v245, v246
	global_store_dwordx4 v247, v[150:153], s[38:39]
	v_add_f32_dpp v246, v246, v246 quad_perm:[1,0,3,2] row_mask:0xf bank_mask:0xf
	s_add_u32 s38, s38, 0x4000
	s_addc_u32 s39, s39, 0
	v_add_f32_dpp v246, v246, v246 quad_perm:[2,3,0,1] row_mask:0xf bank_mask:0xf
	s_nop 1
	v_add_f32_dpp v246, v246, v246 row_half_mirror row_mask:0xf bank_mask:0xf
	s_nop 1
	v_add_f32_dpp v246, v246, v246 row_mirror row_mask:0xf bank_mask:0xf
	s_mov_b64 exec, s[48:49]
	global_store_dword v249, v246, s[34:35] offset:1280
	s_mov_b64 exec, -1
	s_waitcnt vmcnt(37) lgkmcnt(1)
	v_pk_add_f32 v[154:155], v[228:229], v[154:155]
	v_pk_add_f32 v[156:157], v[230:231], v[156:157]
	v_pk_mul_f32 v[232:233], v[154:155], v[154:155]
	v_pk_mul_f32 v[234:235], v[156:157], v[156:157]
	ds_read_b128 v[228:231], v210 offset:8192
	v_add_f32_e32 v236, v232, v233
	v_add_f32_e32 v236, v234, v236
	v_add_f32_e32 v236, v235, v236
	global_store_dwordx4 v247, v[154:157], s[38:39]
	v_add_f32_dpp v236, v236, v236 quad_perm:[1,0,3,2] row_mask:0xf bank_mask:0xf
	s_add_u32 s38, s38, 0x4000
	s_addc_u32 s39, s39, 0
	v_add_f32_dpp v236, v236, v236 quad_perm:[2,3,0,1] row_mask:0xf bank_mask:0xf
	s_nop 1
	v_add_f32_dpp v236, v236, v236 row_half_mirror row_mask:0xf bank_mask:0xf
	s_nop 1
	v_add_f32_dpp v236, v236, v236 row_mirror row_mask:0xf bank_mask:0xf
	s_mov_b64 exec, s[48:49]
	global_store_dword v249, v236, s[34:35] offset:1536
	s_mov_b64 exec, -1
	s_waitcnt vmcnt(38) lgkmcnt(1)
	v_pk_add_f32 v[158:159], v[238:239], v[158:159]
	v_pk_add_f32 v[160:161], v[240:241], v[160:161]
	v_pk_mul_f32 v[242:243], v[158:159], v[158:159]
	v_pk_mul_f32 v[244:245], v[160:161], v[160:161]
	ds_read_b128 v[238:241], v211 offset:9216
	v_add_f32_e32 v246, v242, v243
	v_add_f32_e32 v246, v244, v246
	v_add_f32_e32 v246, v245, v246
	global_store_dwordx4 v247, v[158:161], s[38:39]
	v_add_f32_dpp v246, v246, v246 quad_perm:[1,0,3,2] row_mask:0xf bank_mask:0xf
	s_add_u32 s38, s38, 0x4000
	s_addc_u32 s39, s39, 0
	v_add_f32_dpp v246, v246, v246 quad_perm:[2,3,0,1] row_mask:0xf bank_mask:0xf
	s_nop 1
	v_add_f32_dpp v246, v246, v246 row_half_mirror row_mask:0xf bank_mask:0xf
	s_nop 1
	v_add_f32_dpp v246, v246, v246 row_mirror row_mask:0xf bank_mask:0xf
	s_mov_b64 exec, s[48:49]
	global_store_dword v249, v246, s[34:35] offset:1792
	s_mov_b64 exec, -1
	s_waitcnt vmcnt(39) lgkmcnt(1)
	v_pk_add_f32 v[162:163], v[228:229], v[162:163]
	v_pk_add_f32 v[164:165], v[230:231], v[164:165]
	v_pk_mul_f32 v[232:233], v[162:163], v[162:163]
	v_pk_mul_f32 v[234:235], v[164:165], v[164:165]
	ds_read_b128 v[228:231], v215 offset:10240
	v_add_f32_e32 v236, v232, v233
	v_add_f32_e32 v236, v234, v236
	v_add_f32_e32 v236, v235, v236
	global_store_dwordx4 v247, v[162:165], s[38:39]
	v_add_f32_dpp v236, v236, v236 quad_perm:[1,0,3,2] row_mask:0xf bank_mask:0xf
	s_add_u32 s38, s38, 0x4000
	s_addc_u32 s39, s39, 0
	v_add_f32_dpp v236, v236, v236 quad_perm:[2,3,0,1] row_mask:0xf bank_mask:0xf
	s_nop 1
	v_add_f32_dpp v236, v236, v236 row_half_mirror row_mask:0xf bank_mask:0xf
	s_nop 1
	v_add_f32_dpp v236, v236, v236 row_mirror row_mask:0xf bank_mask:0xf
	s_mov_b64 exec, s[48:49]
	global_store_dword v249, v236, s[34:35] offset:2048
	s_mov_b64 exec, -1
	s_waitcnt vmcnt(40) lgkmcnt(1)
	v_pk_add_f32 v[166:167], v[238:239], v[166:167]
	v_pk_add_f32 v[168:169], v[240:241], v[168:169]
	v_pk_mul_f32 v[242:243], v[166:167], v[166:167]
	v_pk_mul_f32 v[244:245], v[168:169], v[168:169]
	ds_read_b128 v[238:241], v237 offset:11264
	v_add_f32_e32 v246, v242, v243
	v_add_f32_e32 v246, v244, v246
	v_add_f32_e32 v246, v245, v246
	global_store_dwordx4 v247, v[166:169], s[38:39]
	v_add_f32_dpp v246, v246, v246 quad_perm:[1,0,3,2] row_mask:0xf bank_mask:0xf
	s_add_u32 s38, s38, 0x4000
	s_addc_u32 s39, s39, 0
	v_add_f32_dpp v246, v246, v246 quad_perm:[2,3,0,1] row_mask:0xf bank_mask:0xf
	s_nop 1
	v_add_f32_dpp v246, v246, v246 row_half_mirror row_mask:0xf bank_mask:0xf
	s_nop 1
	v_add_f32_dpp v246, v246, v246 row_mirror row_mask:0xf bank_mask:0xf
	s_mov_b64 exec, s[48:49]
	global_store_dword v249, v246, s[34:35] offset:2304
	s_mov_b64 exec, -1
	s_waitcnt vmcnt(41) lgkmcnt(1)
	v_pk_add_f32 v[192:193], v[228:229], v[192:193]
	v_pk_add_f32 v[194:195], v[230:231], v[194:195]
	v_pk_mul_f32 v[232:233], v[192:193], v[192:193]
	v_pk_mul_f32 v[234:235], v[194:195], v[194:195]
	ds_read_b128 v[228:231], v210 offset:12288
	v_add_f32_e32 v236, v232, v233
	v_add_f32_e32 v236, v234, v236
	v_add_f32_e32 v236, v235, v236
	global_store_dwordx4 v247, v[192:195], s[38:39]
	v_add_f32_dpp v236, v236, v236 quad_perm:[1,0,3,2] row_mask:0xf bank_mask:0xf
	s_add_u32 s38, s38, 0x4000
	s_addc_u32 s39, s39, 0
	v_add_f32_dpp v236, v236, v236 quad_perm:[2,3,0,1] row_mask:0xf bank_mask:0xf
	s_nop 1
	v_add_f32_dpp v236, v236, v236 row_half_mirror row_mask:0xf bank_mask:0xf
	s_nop 1
	v_add_f32_dpp v236, v236, v236 row_mirror row_mask:0xf bank_mask:0xf
	s_mov_b64 exec, s[48:49]
	global_store_dword v249, v236, s[34:35] offset:2560
	s_mov_b64 exec, -1
	s_waitcnt vmcnt(42) lgkmcnt(1)
	v_pk_add_f32 v[196:197], v[238:239], v[196:197]
	v_pk_add_f32 v[198:199], v[240:241], v[198:199]
	v_pk_mul_f32 v[242:243], v[196:197], v[196:197]
	v_pk_mul_f32 v[244:245], v[198:199], v[198:199]
	ds_read_b128 v[238:241], v211 offset:13312
	v_add_f32_e32 v246, v242, v243
	v_add_f32_e32 v246, v244, v246
	v_add_f32_e32 v246, v245, v246
	global_store_dwordx4 v247, v[196:199], s[38:39]
	v_add_f32_dpp v246, v246, v246 quad_perm:[1,0,3,2] row_mask:0xf bank_mask:0xf
	s_add_u32 s38, s38, 0x4000
	s_addc_u32 s39, s39, 0
	v_add_f32_dpp v246, v246, v246 quad_perm:[2,3,0,1] row_mask:0xf bank_mask:0xf
	s_nop 1
	v_add_f32_dpp v246, v246, v246 row_half_mirror row_mask:0xf bank_mask:0xf
	s_nop 1
	v_add_f32_dpp v246, v246, v246 row_mirror row_mask:0xf bank_mask:0xf
	s_mov_b64 exec, s[48:49]
	global_store_dword v249, v246, s[34:35] offset:2816
	s_mov_b64 exec, -1
	s_waitcnt vmcnt(43) lgkmcnt(1)
	v_pk_add_f32 v[200:201], v[228:229], v[200:201]
	v_pk_add_f32 v[202:203], v[230:231], v[202:203]
	v_pk_mul_f32 v[232:233], v[200:201], v[200:201]
	v_pk_mul_f32 v[234:235], v[202:203], v[202:203]
	ds_read_b128 v[228:231], v215 offset:14336
	v_add_f32_e32 v236, v232, v233
	v_add_f32_e32 v236, v234, v236
	v_add_f32_e32 v236, v235, v236
	global_store_dwordx4 v247, v[200:203], s[38:39]
	v_add_f32_dpp v236, v236, v236 quad_perm:[1,0,3,2] row_mask:0xf bank_mask:0xf
	s_add_u32 s38, s38, 0x4000
	s_addc_u32 s39, s39, 0
	v_add_f32_dpp v236, v236, v236 quad_perm:[2,3,0,1] row_mask:0xf bank_mask:0xf
	s_nop 1
	v_add_f32_dpp v236, v236, v236 row_half_mirror row_mask:0xf bank_mask:0xf
	s_nop 1
	v_add_f32_dpp v236, v236, v236 row_mirror row_mask:0xf bank_mask:0xf
	s_mov_b64 exec, s[48:49]
	global_store_dword v249, v236, s[34:35] offset:3072
	s_mov_b64 exec, -1
	s_waitcnt vmcnt(44) lgkmcnt(1)
	v_pk_add_f32 v[216:217], v[238:239], v[216:217]
	v_pk_add_f32 v[218:219], v[240:241], v[218:219]
	v_pk_mul_f32 v[242:243], v[216:217], v[216:217]
	v_pk_mul_f32 v[244:245], v[218:219], v[218:219]
	ds_read_b128 v[238:241], v237 offset:15360
	v_add_f32_e32 v246, v242, v243
	v_add_f32_e32 v246, v244, v246
	v_add_f32_e32 v246, v245, v246
	global_store_dwordx4 v247, v[216:219], s[38:39]
	v_add_f32_dpp v246, v246, v246 quad_perm:[1,0,3,2] row_mask:0xf bank_mask:0xf
	s_add_u32 s38, s38, 0x4000
	s_addc_u32 s39, s39, 0
	v_add_f32_dpp v246, v246, v246 quad_perm:[2,3,0,1] row_mask:0xf bank_mask:0xf
	s_nop 1
	v_add_f32_dpp v246, v246, v246 row_half_mirror row_mask:0xf bank_mask:0xf
	s_nop 1
	v_add_f32_dpp v246, v246, v246 row_mirror row_mask:0xf bank_mask:0xf
	s_mov_b64 exec, s[48:49]
	global_store_dword v249, v246, s[34:35] offset:3328
	s_mov_b64 exec, -1
	s_waitcnt vmcnt(45) lgkmcnt(1)
	v_pk_add_f32 v[220:221], v[228:229], v[220:221]
	v_pk_add_f32 v[222:223], v[230:231], v[222:223]
	v_pk_mul_f32 v[232:233], v[220:221], v[220:221]
	v_pk_mul_f32 v[234:235], v[222:223], v[222:223]
	v_add_f32_e32 v236, v232, v233
	v_add_f32_e32 v236, v234, v236
	v_add_f32_e32 v236, v235, v236
	global_store_dwordx4 v247, v[220:223], s[38:39]
	v_add_f32_dpp v236, v236, v236 quad_perm:[1,0,3,2] row_mask:0xf bank_mask:0xf
	s_add_u32 s38, s38, 0x4000
	s_addc_u32 s39, s39, 0
	v_add_f32_dpp v236, v236, v236 quad_perm:[2,3,0,1] row_mask:0xf bank_mask:0xf
	s_nop 1
	v_add_f32_dpp v236, v236, v236 row_half_mirror row_mask:0xf bank_mask:0xf
	s_nop 1
	v_add_f32_dpp v236, v236, v236 row_mirror row_mask:0xf bank_mask:0xf
	s_mov_b64 exec, s[48:49]
	global_store_dword v249, v236, s[34:35] offset:3584
	s_mov_b64 exec, -1
	s_waitcnt vmcnt(46) lgkmcnt(0)
	v_pk_add_f32 v[224:225], v[238:239], v[224:225]
	v_pk_add_f32 v[226:227], v[240:241], v[226:227]
	v_pk_mul_f32 v[242:243], v[224:225], v[224:225]
	v_pk_mul_f32 v[244:245], v[226:227], v[226:227]
	v_add_f32_e32 v246, v242, v243
	v_add_f32_e32 v246, v244, v246
	v_add_f32_e32 v246, v245, v246
	global_store_dwordx4 v247, v[224:227], s[38:39]
	v_add_f32_dpp v246, v246, v246 quad_perm:[1,0,3,2] row_mask:0xf bank_mask:0xf
	s_add_u32 s38, s38, 0x4000
	s_addc_u32 s39, s39, 0
	v_add_f32_dpp v246, v246, v246 quad_perm:[2,3,0,1] row_mask:0xf bank_mask:0xf
	s_nop 1
	v_add_f32_dpp v246, v246, v246 row_half_mirror row_mask:0xf bank_mask:0xf
	s_nop 1
	v_add_f32_dpp v246, v246, v246 row_mirror row_mask:0xf bank_mask:0xf
	s_mov_b64 exec, s[48:49]
	global_store_dword v249, v246, s[34:35] offset:3840
	s_mov_b64 exec, -1
	s_add_u32 s34, s34, 0x1000
	s_addc_u32 s35, s35, 0
	v_and_b32_e32 v238, 15, v170
	v_xor_b32_e32 v238, v238, v171
	v_lshl_add_u32 v239, v170, 8, s40
	v_xor_b32_e32 v228, 0, v238
	v_lshl_add_u32 v228, v228, 4, v239
	v_xor_b32_e32 v229, 2, v238
	v_lshl_add_u32 v229, v229, 4, v239
	v_xor_b32_e32 v230, 4, v238
	v_lshl_add_u32 v230, v230, 4, v239
	v_xor_b32_e32 v231, 6, v238
	v_lshl_add_u32 v231, v231, 4, v239
	v_xor_b32_e32 v232, 8, v238
	v_lshl_add_u32 v232, v232, 4, v239
	v_xor_b32_e32 v233, 10, v238
	v_lshl_add_u32 v233, v233, 4, v239
	v_xor_b32_e32 v234, 12, v238
	v_lshl_add_u32 v234, v234, 4, v239
	v_xor_b32_e32 v235, 14, v238
	v_lshl_add_u32 v235, v235, 4, v239
	ds_write_b128 v228, v[18:21]
	ds_write_b128 v229, v[22:25]
	ds_write_b128 v230, v[26:29]
	ds_write_b128 v231, v[30:33]
	ds_write_b128 v232, v[50:53]
	ds_write_b128 v233, v[54:57]
	ds_write_b128 v234, v[58:61]
	ds_write_b128 v235, v[62:65]
	ds_write_b128 v228, v[2:5] offset:8192
	ds_write_b128 v229, v[6:9] offset:8192
	ds_write_b128 v230, v[10:13] offset:8192
	ds_write_b128 v231, v[14:17] offset:8192
	ds_write_b128 v232, v[34:37] offset:8192
	ds_write_b128 v233, v[38:41] offset:8192
	ds_write_b128 v234, v[42:45] offset:8192
	ds_write_b128 v235, v[46:49] offset:8192
	s_waitcnt lgkmcnt(0)
	ds_read_b128 v[228:231], v210 offset:0
	ds_read_b128 v[238:241], v211 offset:1024
	s_waitcnt vmcnt(47) lgkmcnt(1)
	v_pk_add_f32 v[66:67], v[228:229], v[66:67]
	v_pk_add_f32 v[68:69], v[230:231], v[68:69]
	v_pk_mul_f32 v[232:233], v[66:67], v[66:67]
	v_pk_mul_f32 v[234:235], v[68:69], v[68:69]
	ds_read_b128 v[228:231], v215 offset:2048
	v_add_f32_e32 v236, v232, v233
	v_add_f32_e32 v236, v234, v236
	v_add_f32_e32 v236, v235, v236
	global_store_dwordx4 v247, v[66:69], s[38:39]
	v_add_f32_dpp v236, v236, v236 quad_perm:[1,0,3,2] row_mask:0xf bank_mask:0xf
	s_add_u32 s38, s38, 0x4000
	s_addc_u32 s39, s39, 0
	v_add_f32_dpp v236, v236, v236 quad_perm:[2,3,0,1] row_mask:0xf bank_mask:0xf
	s_nop 1
	v_add_f32_dpp v236, v236, v236 row_half_mirror row_mask:0xf bank_mask:0xf
	s_nop 1
	v_add_f32_dpp v236, v236, v236 row_mirror row_mask:0xf bank_mask:0xf
	s_mov_b64 exec, s[48:49]
	global_store_dword v249, v236, s[34:35] offset:0
	s_mov_b64 exec, -1
	s_waitcnt vmcnt(48) lgkmcnt(1)
	v_pk_add_f32 v[70:71], v[238:239], v[70:71]
	v_pk_add_f32 v[72:73], v[240:241], v[72:73]
	v_pk_mul_f32 v[242:243], v[70:71], v[70:71]
	v_pk_mul_f32 v[244:245], v[72:73], v[72:73]
	ds_read_b128 v[238:241], v237 offset:3072
	v_add_f32_e32 v246, v242, v243
	v_add_f32_e32 v246, v244, v246
	v_add_f32_e32 v246, v245, v246
	global_store_dwordx4 v247, v[70:73], s[38:39]
	v_add_f32_dpp v246, v246, v246 quad_perm:[1,0,3,2] row_mask:0xf bank_mask:0xf
	s_add_u32 s38, s38, 0x4000
	s_addc_u32 s39, s39, 0
	v_add_f32_dpp v246, v246, v246 quad_perm:[2,3,0,1] row_mask:0xf bank_mask:0xf
	s_nop 1
	v_add_f32_dpp v246, v246, v246 row_half_mirror row_mask:0xf bank_mask:0xf
	s_nop 1
	v_add_f32_dpp v246, v246, v246 row_mirror row_mask:0xf bank_mask:0xf
	s_mov_b64 exec, s[48:49]
	global_store_dword v249, v246, s[34:35] offset:256
	s_mov_b64 exec, -1
	s_waitcnt vmcnt(49) lgkmcnt(1)
	v_pk_add_f32 v[74:75], v[228:229], v[74:75]
	v_pk_add_f32 v[76:77], v[230:231], v[76:77]
	v_pk_mul_f32 v[232:233], v[74:75], v[74:75]
	v_pk_mul_f32 v[234:235], v[76:77], v[76:77]
	ds_read_b128 v[228:231], v210 offset:4096
	v_add_f32_e32 v236, v232, v233
	v_add_f32_e32 v236, v234, v236
	v_add_f32_e32 v236, v235, v236
	global_store_dwordx4 v247, v[74:77], s[38:39]
	v_add_f32_dpp v236, v236, v236 quad_perm:[1,0,3,2] row_mask:0xf bank_mask:0xf
	s_add_u32 s38, s38, 0x4000
	s_addc_u32 s39, s39, 0
	v_add_f32_dpp v236, v236, v236 quad_perm:[2,3,0,1] row_mask:0xf bank_mask:0xf
	s_nop 1
	v_add_f32_dpp v236, v236, v236 row_half_mirror row_mask:0xf bank_mask:0xf
	s_nop 1
	v_add_f32_dpp v236, v236, v236 row_mirror row_mask:0xf bank_mask:0xf
	s_mov_b64 exec, s[48:49]
	global_store_dword v249, v236, s[34:35] offset:512
	s_mov_b64 exec, -1
	s_waitcnt vmcnt(50) lgkmcnt(1)
	v_pk_add_f32 v[78:79], v[238:239], v[78:79]
	v_pk_add_f32 v[80:81], v[240:241], v[80:81]
	v_pk_mul_f32 v[242:243], v[78:79], v[78:79]
	v_pk_mul_f32 v[244:245], v[80:81], v[80:81]
	ds_read_b128 v[238:241], v211 offset:5120
	v_add_f32_e32 v246, v242, v243
	v_add_f32_e32 v246, v244, v246
	v_add_f32_e32 v246, v245, v246
	global_store_dwordx4 v247, v[78:81], s[38:39]
	v_add_f32_dpp v246, v246, v246 quad_perm:[1,0,3,2] row_mask:0xf bank_mask:0xf
	s_add_u32 s38, s38, 0x4000
	s_addc_u32 s39, s39, 0
	v_add_f32_dpp v246, v246, v246 quad_perm:[2,3,0,1] row_mask:0xf bank_mask:0xf
	s_nop 1
	v_add_f32_dpp v246, v246, v246 row_half_mirror row_mask:0xf bank_mask:0xf
	s_nop 1
	v_add_f32_dpp v246, v246, v246 row_mirror row_mask:0xf bank_mask:0xf
	s_mov_b64 exec, s[48:49]
	global_store_dword v249, v246, s[34:35] offset:768
	s_mov_b64 exec, -1
	s_waitcnt vmcnt(51) lgkmcnt(1)
	v_pk_add_f32 v[114:115], v[228:229], v[114:115]
	v_pk_add_f32 v[116:117], v[230:231], v[116:117]
	v_pk_mul_f32 v[232:233], v[114:115], v[114:115]
	v_pk_mul_f32 v[234:235], v[116:117], v[116:117]
	ds_read_b128 v[228:231], v215 offset:6144
	v_add_f32_e32 v236, v232, v233
	v_add_f32_e32 v236, v234, v236
	v_add_f32_e32 v236, v235, v236
	global_store_dwordx4 v247, v[114:117], s[38:39]
	v_add_f32_dpp v236, v236, v236 quad_perm:[1,0,3,2] row_mask:0xf bank_mask:0xf
	s_add_u32 s38, s38, 0x4000
	s_addc_u32 s39, s39, 0
	v_add_f32_dpp v236, v236, v236 quad_perm:[2,3,0,1] row_mask:0xf bank_mask:0xf
	s_nop 1
	v_add_f32_dpp v236, v236, v236 row_half_mirror row_mask:0xf bank_mask:0xf
	s_nop 1
	v_add_f32_dpp v236, v236, v236 row_mirror row_mask:0xf bank_mask:0xf
	s_mov_b64 exec, s[48:49]
	global_store_dword v249, v236, s[34:35] offset:1024
	s_mov_b64 exec, -1
	s_waitcnt vmcnt(52) lgkmcnt(1)
	v_pk_add_f32 v[118:119], v[238:239], v[118:119]
	v_pk_add_f32 v[120:121], v[240:241], v[120:121]
	v_pk_mul_f32 v[242:243], v[118:119], v[118:119]
	v_pk_mul_f32 v[244:245], v[120:121], v[120:121]
	ds_read_b128 v[238:241], v237 offset:7168
	v_add_f32_e32 v246, v242, v243
	v_add_f32_e32 v246, v244, v246
	v_add_f32_e32 v246, v245, v246
	global_store_dwordx4 v247, v[118:121], s[38:39]
	v_add_f32_dpp v246, v246, v246 quad_perm:[1,0,3,2] row_mask:0xf bank_mask:0xf
	s_add_u32 s38, s38, 0x4000
	s_addc_u32 s39, s39, 0
	v_add_f32_dpp v246, v246, v246 quad_perm:[2,3,0,1] row_mask:0xf bank_mask:0xf
	s_nop 1
	v_add_f32_dpp v246, v246, v246 row_half_mirror row_mask:0xf bank_mask:0xf
	s_nop 1
	v_add_f32_dpp v246, v246, v246 row_mirror row_mask:0xf bank_mask:0xf
	s_mov_b64 exec, s[48:49]
	global_store_dword v249, v246, s[34:35] offset:1280
	s_mov_b64 exec, -1
	s_waitcnt vmcnt(53) lgkmcnt(1)
	v_pk_add_f32 v[122:123], v[228:229], v[122:123]
	v_pk_add_f32 v[124:125], v[230:231], v[124:125]
	v_pk_mul_f32 v[232:233], v[122:123], v[122:123]
	v_pk_mul_f32 v[234:235], v[124:125], v[124:125]
	ds_read_b128 v[228:231], v210 offset:8192
	v_add_f32_e32 v236, v232, v233
	v_add_f32_e32 v236, v234, v236
	v_add_f32_e32 v236, v235, v236
	global_store_dwordx4 v247, v[122:125], s[38:39]
	v_add_f32_dpp v236, v236, v236 quad_perm:[1,0,3,2] row_mask:0xf bank_mask:0xf
	s_add_u32 s38, s38, 0x4000
	s_addc_u32 s39, s39, 0
	v_add_f32_dpp v236, v236, v236 quad_perm:[2,3,0,1] row_mask:0xf bank_mask:0xf
	s_nop 1
	v_add_f32_dpp v236, v236, v236 row_half_mirror row_mask:0xf bank_mask:0xf
	s_nop 1
	v_add_f32_dpp v236, v236, v236 row_mirror row_mask:0xf bank_mask:0xf
	s_mov_b64 exec, s[48:49]
	global_store_dword v249, v236, s[34:35] offset:1536
	s_mov_b64 exec, -1
	s_waitcnt vmcnt(54) lgkmcnt(1)
	v_pk_add_f32 v[126:127], v[238:239], v[126:127]
	v_pk_add_f32 v[128:129], v[240:241], v[128:129]
	v_pk_mul_f32 v[242:243], v[126:127], v[126:127]
	v_pk_mul_f32 v[244:245], v[128:129], v[128:129]
	ds_read_b128 v[238:241], v211 offset:9216
	v_add_f32_e32 v246, v242, v243
	v_add_f32_e32 v246, v244, v246
	v_add_f32_e32 v246, v245, v246
	global_store_dwordx4 v247, v[126:129], s[38:39]
	v_add_f32_dpp v246, v246, v246 quad_perm:[1,0,3,2] row_mask:0xf bank_mask:0xf
	s_add_u32 s38, s38, 0x4000
	s_addc_u32 s39, s39, 0
	v_add_f32_dpp v246, v246, v246 quad_perm:[2,3,0,1] row_mask:0xf bank_mask:0xf
	s_nop 1
	v_add_f32_dpp v246, v246, v246 row_half_mirror row_mask:0xf bank_mask:0xf
	s_nop 1
	v_add_f32_dpp v246, v246, v246 row_mirror row_mask:0xf bank_mask:0xf
	s_mov_b64 exec, s[48:49]
	global_store_dword v249, v246, s[34:35] offset:1792
	s_mov_b64 exec, -1
	s_waitcnt vmcnt(55) lgkmcnt(1)
	v_pk_add_f32 v[82:83], v[228:229], v[82:83]
	v_pk_add_f32 v[84:85], v[230:231], v[84:85]
	v_pk_mul_f32 v[232:233], v[82:83], v[82:83]
	v_pk_mul_f32 v[234:235], v[84:85], v[84:85]
	ds_read_b128 v[228:231], v215 offset:10240
	v_add_f32_e32 v236, v232, v233
	v_add_f32_e32 v236, v234, v236
	v_add_f32_e32 v236, v235, v236
	global_store_dwordx4 v247, v[82:85], s[38:39]
	v_add_f32_dpp v236, v236, v236 quad_perm:[1,0,3,2] row_mask:0xf bank_mask:0xf
	s_add_u32 s38, s38, 0x4000
	s_addc_u32 s39, s39, 0
	v_add_f32_dpp v236, v236, v236 quad_perm:[2,3,0,1] row_mask:0xf bank_mask:0xf
	s_nop 1
	v_add_f32_dpp v236, v236, v236 row_half_mirror row_mask:0xf bank_mask:0xf
	s_nop 1
	v_add_f32_dpp v236, v236, v236 row_mirror row_mask:0xf bank_mask:0xf
	s_mov_b64 exec, s[48:49]
	global_store_dword v249, v236, s[34:35] offset:2048
	s_mov_b64 exec, -1
	s_waitcnt vmcnt(56) lgkmcnt(1)
	v_pk_add_f32 v[86:87], v[238:239], v[86:87]
	v_pk_add_f32 v[88:89], v[240:241], v[88:89]
	v_pk_mul_f32 v[242:243], v[86:87], v[86:87]
	v_pk_mul_f32 v[244:245], v[88:89], v[88:89]
	ds_read_b128 v[238:241], v237 offset:11264
	v_add_f32_e32 v246, v242, v243
	v_add_f32_e32 v246, v244, v246
	v_add_f32_e32 v246, v245, v246
	global_store_dwordx4 v247, v[86:89], s[38:39]
	v_add_f32_dpp v246, v246, v246 quad_perm:[1,0,3,2] row_mask:0xf bank_mask:0xf
	s_add_u32 s38, s38, 0x4000
	s_addc_u32 s39, s39, 0
	v_add_f32_dpp v246, v246, v246 quad_perm:[2,3,0,1] row_mask:0xf bank_mask:0xf
	s_nop 1
	v_add_f32_dpp v246, v246, v246 row_half_mirror row_mask:0xf bank_mask:0xf
	s_nop 1
	v_add_f32_dpp v246, v246, v246 row_mirror row_mask:0xf bank_mask:0xf
	s_mov_b64 exec, s[48:49]
	global_store_dword v249, v246, s[34:35] offset:2304
	s_mov_b64 exec, -1
	s_waitcnt vmcnt(57) lgkmcnt(1)
	v_pk_add_f32 v[90:91], v[228:229], v[90:91]
	v_pk_add_f32 v[92:93], v[230:231], v[92:93]
	v_pk_mul_f32 v[232:233], v[90:91], v[90:91]
	v_pk_mul_f32 v[234:235], v[92:93], v[92:93]
	ds_read_b128 v[228:231], v210 offset:12288
	v_add_f32_e32 v236, v232, v233
	v_add_f32_e32 v236, v234, v236
	v_add_f32_e32 v236, v235, v236
	global_store_dwordx4 v247, v[90:93], s[38:39]
	v_add_f32_dpp v236, v236, v236 quad_perm:[1,0,3,2] row_mask:0xf bank_mask:0xf
	s_add_u32 s38, s38, 0x4000
	s_addc_u32 s39, s39, 0
	v_add_f32_dpp v236, v236, v236 quad_perm:[2,3,0,1] row_mask:0xf bank_mask:0xf
	s_nop 1
	v_add_f32_dpp v236, v236, v236 row_half_mirror row_mask:0xf bank_mask:0xf
	s_nop 1
	v_add_f32_dpp v236, v236, v236 row_mirror row_mask:0xf bank_mask:0xf
	s_mov_b64 exec, s[48:49]
	global_store_dword v249, v236, s[34:35] offset:2560
	s_mov_b64 exec, -1
	s_waitcnt vmcnt(58) lgkmcnt(1)
	v_pk_add_f32 v[94:95], v[238:239], v[94:95]
	v_pk_add_f32 v[96:97], v[240:241], v[96:97]
	v_pk_mul_f32 v[242:243], v[94:95], v[94:95]
	v_pk_mul_f32 v[244:245], v[96:97], v[96:97]
	ds_read_b128 v[238:241], v211 offset:13312
	v_add_f32_e32 v246, v242, v243
	v_add_f32_e32 v246, v244, v246
	v_add_f32_e32 v246, v245, v246
	global_store_dwordx4 v247, v[94:97], s[38:39]
	v_add_f32_dpp v246, v246, v246 quad_perm:[1,0,3,2] row_mask:0xf bank_mask:0xf
	s_add_u32 s38, s38, 0x4000
	s_addc_u32 s39, s39, 0
	v_add_f32_dpp v246, v246, v246 quad_perm:[2,3,0,1] row_mask:0xf bank_mask:0xf
	s_nop 1
	v_add_f32_dpp v246, v246, v246 row_half_mirror row_mask:0xf bank_mask:0xf
	s_nop 1
	v_add_f32_dpp v246, v246, v246 row_mirror row_mask:0xf bank_mask:0xf
	s_mov_b64 exec, s[48:49]
	global_store_dword v249, v246, s[34:35] offset:2816
	s_mov_b64 exec, -1
	s_waitcnt vmcnt(59) lgkmcnt(1)
	v_pk_add_f32 v[98:99], v[228:229], v[98:99]
	v_pk_add_f32 v[100:101], v[230:231], v[100:101]
	v_pk_mul_f32 v[232:233], v[98:99], v[98:99]
	v_pk_mul_f32 v[234:235], v[100:101], v[100:101]
	ds_read_b128 v[228:231], v215 offset:14336
	v_add_f32_e32 v236, v232, v233
	v_add_f32_e32 v236, v234, v236
	v_add_f32_e32 v236, v235, v236
	global_store_dwordx4 v247, v[98:101], s[38:39]
	v_add_f32_dpp v236, v236, v236 quad_perm:[1,0,3,2] row_mask:0xf bank_mask:0xf
	s_add_u32 s38, s38, 0x4000
	s_addc_u32 s39, s39, 0
	v_add_f32_dpp v236, v236, v236 quad_perm:[2,3,0,1] row_mask:0xf bank_mask:0xf
	s_nop 1
	v_add_f32_dpp v236, v236, v236 row_half_mirror row_mask:0xf bank_mask:0xf
	s_nop 1
	v_add_f32_dpp v236, v236, v236 row_mirror row_mask:0xf bank_mask:0xf
	s_mov_b64 exec, s[48:49]
	global_store_dword v249, v236, s[34:35] offset:3072
	s_mov_b64 exec, -1
	s_waitcnt vmcnt(60) lgkmcnt(1)
	v_pk_add_f32 v[102:103], v[238:239], v[102:103]
	v_pk_add_f32 v[104:105], v[240:241], v[104:105]
	v_pk_mul_f32 v[242:243], v[102:103], v[102:103]
	v_pk_mul_f32 v[244:245], v[104:105], v[104:105]
	ds_read_b128 v[238:241], v237 offset:15360
	v_add_f32_e32 v246, v242, v243
	v_add_f32_e32 v246, v244, v246
	v_add_f32_e32 v246, v245, v246
	global_store_dwordx4 v247, v[102:105], s[38:39]
	v_add_f32_dpp v246, v246, v246 quad_perm:[1,0,3,2] row_mask:0xf bank_mask:0xf
	s_add_u32 s38, s38, 0x4000
	s_addc_u32 s39, s39, 0
	v_add_f32_dpp v246, v246, v246 quad_perm:[2,3,0,1] row_mask:0xf bank_mask:0xf
	s_nop 1
	v_add_f32_dpp v246, v246, v246 row_half_mirror row_mask:0xf bank_mask:0xf
	s_nop 1
	v_add_f32_dpp v246, v246, v246 row_mirror row_mask:0xf bank_mask:0xf
	s_mov_b64 exec, s[48:49]
	global_store_dword v249, v246, s[34:35] offset:3328
	s_mov_b64 exec, -1
	s_waitcnt vmcnt(61) lgkmcnt(1)
	v_pk_add_f32 v[106:107], v[228:229], v[106:107]
	v_pk_add_f32 v[108:109], v[230:231], v[108:109]
	v_pk_mul_f32 v[232:233], v[106:107], v[106:107]
	v_pk_mul_f32 v[234:235], v[108:109], v[108:109]
	v_add_f32_e32 v236, v232, v233
	v_add_f32_e32 v236, v234, v236
	v_add_f32_e32 v236, v235, v236
	global_store_dwordx4 v247, v[106:109], s[38:39]
	v_add_f32_dpp v236, v236, v236 quad_perm:[1,0,3,2] row_mask:0xf bank_mask:0xf
	s_add_u32 s38, s38, 0x4000
	s_addc_u32 s39, s39, 0
	v_add_f32_dpp v236, v236, v236 quad_perm:[2,3,0,1] row_mask:0xf bank_mask:0xf
	s_nop 1
	v_add_f32_dpp v236, v236, v236 row_half_mirror row_mask:0xf bank_mask:0xf
	s_nop 1
	v_add_f32_dpp v236, v236, v236 row_mirror row_mask:0xf bank_mask:0xf
	s_mov_b64 exec, s[48:49]
	global_store_dword v249, v236, s[34:35] offset:3584
	s_mov_b64 exec, -1
	s_waitcnt vmcnt(62) lgkmcnt(0)
	v_pk_add_f32 v[110:111], v[238:239], v[110:111]
	v_pk_add_f32 v[112:113], v[240:241], v[112:113]
	v_pk_mul_f32 v[242:243], v[110:111], v[110:111]
	v_pk_mul_f32 v[244:245], v[112:113], v[112:113]
	v_add_f32_e32 v246, v242, v243
	v_add_f32_e32 v246, v244, v246
	v_add_f32_e32 v246, v245, v246
	global_store_dwordx4 v247, v[110:113], s[38:39]
	v_add_f32_dpp v246, v246, v246 quad_perm:[1,0,3,2] row_mask:0xf bank_mask:0xf
	s_add_u32 s38, s38, 0x4000
	s_addc_u32 s39, s39, 0
	v_add_f32_dpp v246, v246, v246 quad_perm:[2,3,0,1] row_mask:0xf bank_mask:0xf
	s_nop 1
	v_add_f32_dpp v246, v246, v246 row_half_mirror row_mask:0xf bank_mask:0xf
	s_nop 1
	v_add_f32_dpp v246, v246, v246 row_mirror row_mask:0xf bank_mask:0xf
	s_mov_b64 exec, s[48:49]
	global_store_dword v249, v246, s[34:35] offset:3840
	s_mov_b64 exec, -1
	s_waitcnt lgkmcnt(0)
	s_branch .LBB0_1677
